# GEMM K-loops: pair serpentine along the first MFMA operand (runs of four pairs share it)
# speedup vs baseline: 1.0219x; 1.0038x over previous
.LBB0_383:
	s_ashr_i32 s67, s66, 31
	s_lshl_b64 s[26:27], s[66:67], 19
	s_add_u32 s26, s40, s26
	s_addc_u32 s27, s41, s27
	s_and_b64 s[34:35], s[8:9], exec
	s_cselect_b32 s34, s27, s5
	s_cselect_b32 s35, s26, s4
	s_ashr_i32 s29, s28, 31
	s_lshl_b64 s[38:39], s[28:29], 19
	s_add_u32 s62, s10, s38
	s_addc_u32 s63, s11, s39
	s_and_b64 s[38:39], s[8:9], exec
	s_cselect_b32 s29, s63, s83
	s_cselect_b32 s38, s62, s82
	s_add_u32 s39, s82, 0x100
	s_addc_u32 s67, s83, 0
	s_mov_b32 s94, -2
	s_mov_b64 vcc, 0
	v_lshl_add_u64 v[132:133], s[4:5], 0, v[168:169]
	ds_read_b128 v[134:137], v199
	ds_read_b128 v[138:141], v200
	ds_read_b128 v[142:145], v201
	ds_read_b128 v[146:149], v202
	ds_read_b128 v[150:153], v203
	ds_read_b128 v[174:177], v204
	ds_read_b128 v[178:181], v205
	ds_read_b128 v[182:185], v206
	s_add_u32 s24, s4, vcc_lo
	s_addc_u32 s25, s5, vcc_hi
	s_add_u32 s24, s24, 0x100
	s_addc_u32 s25, s25, 0
	s_add_u32 s82, s39, vcc_lo
	s_addc_u32 s83, s67, vcc_hi
	s_cmpk_eq_i32 vcc_lo, 0x700
	s_cselect_b32 s87, s29, s83
	s_cselect_b32 s86, s38, s82
	s_cselect_b32 s83, s34, s25
	s_cselect_b32 s82, s35, s24
	v_lshl_add_u64 v[154:155], v[132:133], 0, vcc
	v_lshl_add_u64 v[250:251], v[154:155], 0, s[48:49]
	s_add_i32 m0, s79, 0x8000
	s_mov_b64 s[24:25], 0x20080
	ds_read_b128 v[218:221], v207
	ds_read_b128 v[222:225], v207 offset:2048
	ds_read_b128 v[226:229], v208
	ds_read_b128 v[230:233], v208 offset:2048
	ds_read_b128 v[234:237], v207 offset:4096
	ds_read_b128 v[238:241], v207 offset:6144
	ds_read_b128 v[242:245], v208 offset:4096
	ds_read_b128 v[246:249], v208 offset:6144
	global_load_lds_dwordx4 v[250:251], off
	v_lshl_add_u64 v[250:251], v[154:155], 0, s[24:25]
	s_add_i32 m0, s79, 0xa000
	s_mov_b64 s[24:25], 0x60080
	global_load_lds_dwordx4 v[250:251], off
	v_lshl_add_u64 v[250:251], v[154:155], 0, s[50:51]
	s_add_i32 m0, s79, 0xc000
	v_lshl_add_u64 v[154:155], v[154:155], 0, s[24:25]
	global_load_lds_dwordx4 v[250:251], off
	s_add_i32 m0, s79, 0xe000
	s_nop 0
	global_load_lds_dwordx4 v[154:155], off
	s_waitcnt lgkmcnt(0)
	s_barrier
	v_mfma_f32_16x16x32_bf16 v[128:131], v[134:137], v[218:221], 0
	v_mfma_f32_16x16x32_bf16 v[128:131], v[138:141], v[226:229], v[128:131]
	v_mfma_f32_16x16x32_bf16 v[112:115], v[134:137], v[222:225], 0
	v_mfma_f32_16x16x32_bf16 v[112:115], v[138:141], v[230:233], v[112:115]
	v_mfma_f32_16x16x32_bf16 v[96:99], v[134:137], v[234:237], 0
	v_mfma_f32_16x16x32_bf16 v[96:99], v[138:141], v[242:245], v[96:99]
	v_mfma_f32_16x16x32_bf16 v[80:83], v[134:137], v[238:241], 0
	v_mfma_f32_16x16x32_bf16 v[80:83], v[138:141], v[246:249], v[80:83]
	v_mfma_f32_16x16x32_bf16 v[76:79], v[142:145], v[238:241], 0
	v_mfma_f32_16x16x32_bf16 v[76:79], v[146:149], v[246:249], v[76:79]
	v_mfma_f32_16x16x32_bf16 v[92:95], v[142:145], v[234:237], 0
	v_mfma_f32_16x16x32_bf16 v[92:95], v[146:149], v[242:245], v[92:95]
	v_mfma_f32_16x16x32_bf16 v[108:111], v[142:145], v[222:225], 0
	v_mfma_f32_16x16x32_bf16 v[108:111], v[146:149], v[230:233], v[108:111]
	v_mfma_f32_16x16x32_bf16 v[124:127], v[142:145], v[218:221], 0
	v_mfma_f32_16x16x32_bf16 v[124:127], v[146:149], v[226:229], v[124:127]
	v_mfma_f32_16x16x32_bf16 v[120:123], v[150:153], v[218:221], 0
	v_mfma_f32_16x16x32_bf16 v[120:123], v[174:177], v[226:229], v[120:123]
	v_mfma_f32_16x16x32_bf16 v[104:107], v[150:153], v[222:225], 0
	v_mfma_f32_16x16x32_bf16 v[104:107], v[174:177], v[230:233], v[104:107]
	v_mfma_f32_16x16x32_bf16 v[88:91], v[150:153], v[234:237], 0
	v_mfma_f32_16x16x32_bf16 v[88:91], v[174:177], v[242:245], v[88:91]
	v_mfma_f32_16x16x32_bf16 v[72:75], v[150:153], v[238:241], 0
	v_mfma_f32_16x16x32_bf16 v[72:75], v[174:177], v[246:249], v[72:75]
	v_mfma_f32_16x16x32_bf16 v[68:71], v[178:181], v[238:241], 0
	v_mfma_f32_16x16x32_bf16 v[68:71], v[182:185], v[246:249], v[68:71]
	v_mfma_f32_16x16x32_bf16 v[84:87], v[178:181], v[234:237], 0
	v_mfma_f32_16x16x32_bf16 v[84:87], v[182:185], v[242:245], v[84:87]
	v_mfma_f32_16x16x32_bf16 v[100:103], v[178:181], v[222:225], 0
	v_mfma_f32_16x16x32_bf16 v[100:103], v[182:185], v[230:233], v[100:103]
	v_mfma_f32_16x16x32_bf16 v[116:119], v[178:181], v[218:221], 0
	v_mfma_f32_16x16x32_bf16 v[116:119], v[182:185], v[226:229], v[116:119]
	s_barrier
	s_add_i32 s24, s1, s77
	v_lshl_add_u64 v[154:155], s[86:87], 0, v[158:159]
	s_mov_b32 m0, s24
	ds_read_b128 v[218:221], v207 offset:16384
	ds_read_b128 v[222:225], v207 offset:18432
	ds_read_b128 v[226:229], v208 offset:16384
	ds_read_b128 v[230:233], v208 offset:18432
	ds_read_b128 v[234:237], v207 offset:20480
	ds_read_b128 v[238:241], v207 offset:22528
	ds_read_b128 v[242:245], v208 offset:20480
	ds_read_b128 v[246:249], v208 offset:22528
	global_load_lds_dwordx4 v[154:155], off
	v_lshl_add_u64 v[250:251], v[154:155], 0, s[14:15]
	s_add_i32 m0, s24, 0x2000
	s_add_i32 s24, s12, s77
	global_load_lds_dwordx4 v[250:251], off
	v_lshl_add_u64 v[250:251], v[154:155], 0, s[16:17]
	s_mov_b32 m0, s24
	s_nop 0
	global_load_lds_dwordx4 v[250:251], off
	v_lshl_add_u64 v[250:251], v[154:155], 0, s[18:19]
	s_add_i32 m0, s24, 0x2000
	s_nop 0
	global_load_lds_dwordx4 v[250:251], off
	s_waitcnt vmcnt(4)
	s_waitcnt lgkmcnt(0)
	s_barrier
	v_mfma_f32_16x16x32_bf16 v[64:67], v[134:137], v[218:221], 0
	v_mfma_f32_16x16x32_bf16 v[64:67], v[138:141], v[226:229], v[64:67]
	v_mfma_f32_16x16x32_bf16 v[48:51], v[134:137], v[222:225], 0
	v_mfma_f32_16x16x32_bf16 v[48:51], v[138:141], v[230:233], v[48:51]
	v_mfma_f32_16x16x32_bf16 v[32:35], v[134:137], v[234:237], 0
	v_mfma_f32_16x16x32_bf16 v[32:35], v[138:141], v[242:245], v[32:35]
	v_mfma_f32_16x16x32_bf16 v[16:19], v[134:137], v[238:241], 0
	v_mfma_f32_16x16x32_bf16 v[16:19], v[138:141], v[246:249], v[16:19]
	v_mfma_f32_16x16x32_bf16 v[12:15], v[142:145], v[238:241], 0
	v_mfma_f32_16x16x32_bf16 v[12:15], v[146:149], v[246:249], v[12:15]
	v_mfma_f32_16x16x32_bf16 v[28:31], v[142:145], v[234:237], 0
	v_mfma_f32_16x16x32_bf16 v[28:31], v[146:149], v[242:245], v[28:31]
	v_mfma_f32_16x16x32_bf16 v[44:47], v[142:145], v[222:225], 0
	v_mfma_f32_16x16x32_bf16 v[44:47], v[146:149], v[230:233], v[44:47]
	v_mfma_f32_16x16x32_bf16 v[60:63], v[142:145], v[218:221], 0
	v_mfma_f32_16x16x32_bf16 v[60:63], v[146:149], v[226:229], v[60:63]
	v_mfma_f32_16x16x32_bf16 v[56:59], v[150:153], v[218:221], 0
	v_mfma_f32_16x16x32_bf16 v[56:59], v[174:177], v[226:229], v[56:59]
	v_mfma_f32_16x16x32_bf16 v[40:43], v[150:153], v[222:225], 0
	v_mfma_f32_16x16x32_bf16 v[40:43], v[174:177], v[230:233], v[40:43]
	v_mfma_f32_16x16x32_bf16 v[24:27], v[150:153], v[234:237], 0
	v_mfma_f32_16x16x32_bf16 v[24:27], v[174:177], v[242:245], v[24:27]
	v_mfma_f32_16x16x32_bf16 v[8:11], v[150:153], v[238:241], 0
	v_mfma_f32_16x16x32_bf16 v[8:11], v[174:177], v[246:249], v[8:11]
	v_mfma_f32_16x16x32_bf16 v[4:7], v[178:181], v[238:241], 0
	v_mfma_f32_16x16x32_bf16 v[4:7], v[182:185], v[246:249], v[4:7]
	v_mfma_f32_16x16x32_bf16 v[20:23], v[178:181], v[234:237], 0
	v_mfma_f32_16x16x32_bf16 v[20:23], v[182:185], v[242:245], v[20:23]
	v_mfma_f32_16x16x32_bf16 v[36:39], v[178:181], v[222:225], 0
	v_mfma_f32_16x16x32_bf16 v[36:39], v[182:185], v[230:233], v[36:39]
	v_mfma_f32_16x16x32_bf16 v[52:55], v[178:181], v[218:221], 0
	v_mfma_f32_16x16x32_bf16 v[52:55], v[182:185], v[226:229], v[52:55]
	s_barrier
	ds_read_b128 v[134:137], v213
	ds_read_b128 v[138:141], v214
	ds_read_b128 v[142:145], v209
	ds_read_b128 v[146:149], v210
	ds_read_b128 v[150:153], v215
	ds_read_b128 v[174:177], v216
	ds_read_b128 v[178:181], v211
	ds_read_b128 v[182:185], v212
	s_mov_b32 m0, s79
	v_lshl_add_u64 v[250:251], s[82:83], 0, v[0:1]
	ds_read_b128 v[218:221], v207 offset:32768
	ds_read_b128 v[222:225], v207 offset:34816
	ds_read_b128 v[226:229], v208 offset:32768
	ds_read_b128 v[230:233], v208 offset:34816
	ds_read_b128 v[234:237], v207 offset:36864
	ds_read_b128 v[238:241], v207 offset:38912
	ds_read_b128 v[242:245], v208 offset:36864
	ds_read_b128 v[246:249], v208 offset:38912
	global_load_lds_dwordx4 v[250:251], off
	v_lshl_add_u64 v[252:253], v[250:251], 0, s[20:21]
	s_mov_b32 m0, s81
	s_nop 0
	global_load_lds_dwordx4 v[252:253], off
	v_lshl_add_u64 v[252:253], v[250:251], 0, s[14:15]
	s_mov_b32 m0, s97
	v_lshl_add_u64 v[250:251], v[250:251], 0, s[22:23]
	global_load_lds_dwordx4 v[252:253], off
	s_mov_b32 m0, s64
	s_nop 0
	global_load_lds_dwordx4 v[250:251], off
	s_waitcnt vmcnt(8)
	s_waitcnt lgkmcnt(0)
	s_barrier
	v_mfma_f32_16x16x32_bf16 v[128:131], v[134:137], v[218:221], v[128:131]
	v_mfma_f32_16x16x32_bf16 v[128:131], v[138:141], v[226:229], v[128:131]
	v_mfma_f32_16x16x32_bf16 v[112:115], v[138:141], v[230:233], v[112:115]
	v_mfma_f32_16x16x32_bf16 v[112:115], v[134:137], v[222:225], v[112:115]
	v_mfma_f32_16x16x32_bf16 v[96:99], v[134:137], v[234:237], v[96:99]
	v_mfma_f32_16x16x32_bf16 v[96:99], v[138:141], v[242:245], v[96:99]
	v_mfma_f32_16x16x32_bf16 v[80:83], v[138:141], v[246:249], v[80:83]
	v_mfma_f32_16x16x32_bf16 v[80:83], v[134:137], v[238:241], v[80:83]
	v_mfma_f32_16x16x32_bf16 v[76:79], v[142:145], v[238:241], v[76:79]
	v_mfma_f32_16x16x32_bf16 v[76:79], v[146:149], v[246:249], v[76:79]
	v_mfma_f32_16x16x32_bf16 v[92:95], v[146:149], v[242:245], v[92:95]
	v_mfma_f32_16x16x32_bf16 v[92:95], v[142:145], v[234:237], v[92:95]
	v_mfma_f32_16x16x32_bf16 v[108:111], v[142:145], v[222:225], v[108:111]
	v_mfma_f32_16x16x32_bf16 v[108:111], v[146:149], v[230:233], v[108:111]
	v_mfma_f32_16x16x32_bf16 v[124:127], v[146:149], v[226:229], v[124:127]
	v_mfma_f32_16x16x32_bf16 v[124:127], v[142:145], v[218:221], v[124:127]
	v_mfma_f32_16x16x32_bf16 v[120:123], v[150:153], v[218:221], v[120:123]
	v_mfma_f32_16x16x32_bf16 v[120:123], v[174:177], v[226:229], v[120:123]
	v_mfma_f32_16x16x32_bf16 v[104:107], v[174:177], v[230:233], v[104:107]
	v_mfma_f32_16x16x32_bf16 v[104:107], v[150:153], v[222:225], v[104:107]
	v_mfma_f32_16x16x32_bf16 v[88:91], v[150:153], v[234:237], v[88:91]
	v_mfma_f32_16x16x32_bf16 v[88:91], v[174:177], v[242:245], v[88:91]
	v_mfma_f32_16x16x32_bf16 v[72:75], v[174:177], v[246:249], v[72:75]
	v_mfma_f32_16x16x32_bf16 v[72:75], v[150:153], v[238:241], v[72:75]
	v_mfma_f32_16x16x32_bf16 v[68:71], v[178:181], v[238:241], v[68:71]
	v_mfma_f32_16x16x32_bf16 v[68:71], v[182:185], v[246:249], v[68:71]
	v_mfma_f32_16x16x32_bf16 v[84:87], v[182:185], v[242:245], v[84:87]
	v_mfma_f32_16x16x32_bf16 v[84:87], v[178:181], v[234:237], v[84:87]
	v_mfma_f32_16x16x32_bf16 v[100:103], v[178:181], v[222:225], v[100:103]
	v_mfma_f32_16x16x32_bf16 v[100:103], v[182:185], v[230:233], v[100:103]
	v_mfma_f32_16x16x32_bf16 v[116:119], v[182:185], v[226:229], v[116:119]
	v_mfma_f32_16x16x32_bf16 v[116:119], v[178:181], v[218:221], v[116:119]
	s_barrier
	s_add_i32 s24, s70, s77
	v_lshl_add_u64 v[250:251], v[154:155], 0, s[48:49]
	s_mov_b32 m0, s24
	ds_read_b128 v[218:221], v207 offset:49152
	ds_read_b128 v[222:225], v207 offset:51200
	ds_read_b128 v[226:229], v208 offset:49152
	ds_read_b128 v[230:233], v208 offset:51200
	ds_read_b128 v[234:237], v207 offset:53248
	ds_read_b128 v[238:241], v207 offset:55296
	ds_read_b128 v[242:245], v208 offset:53248
	ds_read_b128 v[246:249], v208 offset:55296
	global_load_lds_dwordx4 v[250:251], off
	v_lshl_add_u64 v[250:251], v[154:155], 0, s[50:51]
	s_add_i32 m0, s24, 0x2000
	s_add_i32 s24, s71, s77
	global_load_lds_dwordx4 v[250:251], off
	v_lshl_add_u64 v[250:251], v[154:155], 0, s[52:53]
	s_mov_b32 m0, s24
	v_lshl_add_u64 v[154:155], v[154:155], 0, s[54:55]
	global_load_lds_dwordx4 v[250:251], off
	s_add_i32 m0, s24, 0x2000
	s_nop 0
	global_load_lds_dwordx4 v[154:155], off
	s_waitcnt vmcnt(4)
	s_waitcnt lgkmcnt(0)
	s_barrier
	v_mfma_f32_16x16x32_bf16 v[64:67], v[134:137], v[218:221], v[64:67]
	v_mfma_f32_16x16x32_bf16 v[64:67], v[138:141], v[226:229], v[64:67]
	v_mfma_f32_16x16x32_bf16 v[48:51], v[138:141], v[230:233], v[48:51]
	v_mfma_f32_16x16x32_bf16 v[48:51], v[134:137], v[222:225], v[48:51]
	v_mfma_f32_16x16x32_bf16 v[32:35], v[134:137], v[234:237], v[32:35]
	v_mfma_f32_16x16x32_bf16 v[32:35], v[138:141], v[242:245], v[32:35]
	v_mfma_f32_16x16x32_bf16 v[16:19], v[138:141], v[246:249], v[16:19]
	v_mfma_f32_16x16x32_bf16 v[16:19], v[134:137], v[238:241], v[16:19]
	v_mfma_f32_16x16x32_bf16 v[12:15], v[142:145], v[238:241], v[12:15]
	v_mfma_f32_16x16x32_bf16 v[12:15], v[146:149], v[246:249], v[12:15]
	v_mfma_f32_16x16x32_bf16 v[28:31], v[146:149], v[242:245], v[28:31]
	v_mfma_f32_16x16x32_bf16 v[28:31], v[142:145], v[234:237], v[28:31]
	v_mfma_f32_16x16x32_bf16 v[44:47], v[142:145], v[222:225], v[44:47]
	v_mfma_f32_16x16x32_bf16 v[44:47], v[146:149], v[230:233], v[44:47]
	v_mfma_f32_16x16x32_bf16 v[60:63], v[146:149], v[226:229], v[60:63]
	v_mfma_f32_16x16x32_bf16 v[60:63], v[142:145], v[218:221], v[60:63]
	v_mfma_f32_16x16x32_bf16 v[56:59], v[150:153], v[218:221], v[56:59]
	v_mfma_f32_16x16x32_bf16 v[56:59], v[174:177], v[226:229], v[56:59]
	v_mfma_f32_16x16x32_bf16 v[40:43], v[174:177], v[230:233], v[40:43]
	v_mfma_f32_16x16x32_bf16 v[40:43], v[150:153], v[222:225], v[40:43]
	v_mfma_f32_16x16x32_bf16 v[24:27], v[150:153], v[234:237], v[24:27]
	v_mfma_f32_16x16x32_bf16 v[24:27], v[174:177], v[242:245], v[24:27]
	v_mfma_f32_16x16x32_bf16 v[8:11], v[174:177], v[246:249], v[8:11]
	v_mfma_f32_16x16x32_bf16 v[8:11], v[150:153], v[238:241], v[8:11]
	v_mfma_f32_16x16x32_bf16 v[4:7], v[178:181], v[238:241], v[4:7]
	v_mfma_f32_16x16x32_bf16 v[4:7], v[182:185], v[246:249], v[4:7]
	v_mfma_f32_16x16x32_bf16 v[20:23], v[182:185], v[242:245], v[20:23]
	v_mfma_f32_16x16x32_bf16 v[20:23], v[178:181], v[234:237], v[20:23]
	v_mfma_f32_16x16x32_bf16 v[36:39], v[178:181], v[222:225], v[36:39]
	v_mfma_f32_16x16x32_bf16 v[36:39], v[182:185], v[230:233], v[36:39]
	v_mfma_f32_16x16x32_bf16 v[52:55], v[182:185], v[226:229], v[52:55]
	v_mfma_f32_16x16x32_bf16 v[52:55], v[178:181], v[218:221], v[52:55]
	s_barrier
	s_add_i32 s94, s94, 2
	s_add_u32 vcc_lo, vcc_lo, 0x100
	s_addc_u32 vcc_hi, vcc_hi, 0
	s_cmp_gt_u32 s94, 13
.LBB0_384:
	ds_read_b128 v[134:137], v199
	ds_read_b128 v[138:141], v200
	ds_read_b128 v[142:145], v201
	ds_read_b128 v[146:149], v202
	ds_read_b128 v[150:153], v203
	ds_read_b128 v[174:177], v204
	ds_read_b128 v[178:181], v205
	ds_read_b128 v[182:185], v206
	s_add_u32 s24, s4, vcc_lo
	s_addc_u32 s25, s5, vcc_hi
	s_add_u32 s24, s24, 0x100
	s_addc_u32 s25, s25, 0
	s_add_u32 s82, s39, vcc_lo
	s_addc_u32 s83, s67, vcc_hi
	s_cmpk_eq_i32 vcc_lo, 0x700
	s_cselect_b32 s87, s29, s83
	s_cselect_b32 s86, s38, s82
	s_cselect_b32 s83, s34, s25
	s_cselect_b32 s82, s35, s24
	v_lshl_add_u64 v[154:155], v[132:133], 0, vcc
	v_lshl_add_u64 v[250:251], v[154:155], 0, s[48:49]
	s_add_i32 m0, s79, 0x8000
	s_mov_b64 s[24:25], 0x20080
	ds_read_b128 v[218:221], v207
	ds_read_b128 v[222:225], v207 offset:2048
	ds_read_b128 v[226:229], v208
	ds_read_b128 v[230:233], v208 offset:2048
	ds_read_b128 v[234:237], v207 offset:4096
	ds_read_b128 v[238:241], v207 offset:6144
	ds_read_b128 v[242:245], v208 offset:4096
	ds_read_b128 v[246:249], v208 offset:6144
	global_load_lds_dwordx4 v[250:251], off
	v_lshl_add_u64 v[250:251], v[154:155], 0, s[24:25]
	s_add_i32 m0, s79, 0xa000
	s_mov_b64 s[24:25], 0x60080
	global_load_lds_dwordx4 v[250:251], off
	v_lshl_add_u64 v[250:251], v[154:155], 0, s[50:51]
	s_add_i32 m0, s79, 0xc000
	v_lshl_add_u64 v[154:155], v[154:155], 0, s[24:25]
	global_load_lds_dwordx4 v[250:251], off
	s_add_i32 m0, s79, 0xe000
	s_nop 0
	global_load_lds_dwordx4 v[154:155], off
	s_waitcnt vmcnt(8)
	s_waitcnt lgkmcnt(0)
	s_barrier
	v_mfma_f32_16x16x32_bf16 v[128:131], v[134:137], v[218:221], v[128:131]
	v_mfma_f32_16x16x32_bf16 v[128:131], v[138:141], v[226:229], v[128:131]
	v_mfma_f32_16x16x32_bf16 v[112:115], v[138:141], v[230:233], v[112:115]
	v_mfma_f32_16x16x32_bf16 v[112:115], v[134:137], v[222:225], v[112:115]
	v_mfma_f32_16x16x32_bf16 v[96:99], v[134:137], v[234:237], v[96:99]
	v_mfma_f32_16x16x32_bf16 v[96:99], v[138:141], v[242:245], v[96:99]
	v_mfma_f32_16x16x32_bf16 v[80:83], v[138:141], v[246:249], v[80:83]
	v_mfma_f32_16x16x32_bf16 v[80:83], v[134:137], v[238:241], v[80:83]
	v_mfma_f32_16x16x32_bf16 v[76:79], v[142:145], v[238:241], v[76:79]
	v_mfma_f32_16x16x32_bf16 v[76:79], v[146:149], v[246:249], v[76:79]
	v_mfma_f32_16x16x32_bf16 v[92:95], v[146:149], v[242:245], v[92:95]
	v_mfma_f32_16x16x32_bf16 v[92:95], v[142:145], v[234:237], v[92:95]
	v_mfma_f32_16x16x32_bf16 v[108:111], v[142:145], v[222:225], v[108:111]
	v_mfma_f32_16x16x32_bf16 v[108:111], v[146:149], v[230:233], v[108:111]
	v_mfma_f32_16x16x32_bf16 v[124:127], v[146:149], v[226:229], v[124:127]
	v_mfma_f32_16x16x32_bf16 v[124:127], v[142:145], v[218:221], v[124:127]
	v_mfma_f32_16x16x32_bf16 v[120:123], v[150:153], v[218:221], v[120:123]
	v_mfma_f32_16x16x32_bf16 v[120:123], v[174:177], v[226:229], v[120:123]
	v_mfma_f32_16x16x32_bf16 v[104:107], v[174:177], v[230:233], v[104:107]
	v_mfma_f32_16x16x32_bf16 v[104:107], v[150:153], v[222:225], v[104:107]
	v_mfma_f32_16x16x32_bf16 v[88:91], v[150:153], v[234:237], v[88:91]
	v_mfma_f32_16x16x32_bf16 v[88:91], v[174:177], v[242:245], v[88:91]
	v_mfma_f32_16x16x32_bf16 v[72:75], v[174:177], v[246:249], v[72:75]
	v_mfma_f32_16x16x32_bf16 v[72:75], v[150:153], v[238:241], v[72:75]
	v_mfma_f32_16x16x32_bf16 v[68:71], v[178:181], v[238:241], v[68:71]
	v_mfma_f32_16x16x32_bf16 v[68:71], v[182:185], v[246:249], v[68:71]
	v_mfma_f32_16x16x32_bf16 v[84:87], v[182:185], v[242:245], v[84:87]
	v_mfma_f32_16x16x32_bf16 v[84:87], v[178:181], v[234:237], v[84:87]
	v_mfma_f32_16x16x32_bf16 v[100:103], v[178:181], v[222:225], v[100:103]
	v_mfma_f32_16x16x32_bf16 v[100:103], v[182:185], v[230:233], v[100:103]
	v_mfma_f32_16x16x32_bf16 v[116:119], v[182:185], v[226:229], v[116:119]
	v_mfma_f32_16x16x32_bf16 v[116:119], v[178:181], v[218:221], v[116:119]
	s_barrier
	s_add_i32 s24, s1, s77
	v_lshl_add_u64 v[154:155], s[86:87], 0, v[158:159]
	s_mov_b32 m0, s24
	ds_read_b128 v[218:221], v207 offset:16384
	ds_read_b128 v[222:225], v207 offset:18432
	ds_read_b128 v[226:229], v208 offset:16384
	ds_read_b128 v[230:233], v208 offset:18432
	ds_read_b128 v[234:237], v207 offset:20480
	ds_read_b128 v[238:241], v207 offset:22528
	ds_read_b128 v[242:245], v208 offset:20480
	ds_read_b128 v[246:249], v208 offset:22528
	global_load_lds_dwordx4 v[154:155], off
	v_lshl_add_u64 v[250:251], v[154:155], 0, s[14:15]
	s_add_i32 m0, s24, 0x2000
	s_add_i32 s24, s12, s77
	global_load_lds_dwordx4 v[250:251], off
	v_lshl_add_u64 v[250:251], v[154:155], 0, s[16:17]
	s_mov_b32 m0, s24
	s_nop 0
	global_load_lds_dwordx4 v[250:251], off
	v_lshl_add_u64 v[250:251], v[154:155], 0, s[18:19]
	s_add_i32 m0, s24, 0x2000
	s_nop 0
	global_load_lds_dwordx4 v[250:251], off
	s_waitcnt vmcnt(4)
	s_waitcnt lgkmcnt(0)
	s_barrier
	v_mfma_f32_16x16x32_bf16 v[64:67], v[134:137], v[218:221], v[64:67]
	v_mfma_f32_16x16x32_bf16 v[64:67], v[138:141], v[226:229], v[64:67]
	v_mfma_f32_16x16x32_bf16 v[48:51], v[138:141], v[230:233], v[48:51]
	v_mfma_f32_16x16x32_bf16 v[48:51], v[134:137], v[222:225], v[48:51]
	v_mfma_f32_16x16x32_bf16 v[32:35], v[134:137], v[234:237], v[32:35]
	v_mfma_f32_16x16x32_bf16 v[32:35], v[138:141], v[242:245], v[32:35]
	v_mfma_f32_16x16x32_bf16 v[16:19], v[138:141], v[246:249], v[16:19]
	v_mfma_f32_16x16x32_bf16 v[16:19], v[134:137], v[238:241], v[16:19]
	v_mfma_f32_16x16x32_bf16 v[12:15], v[142:145], v[238:241], v[12:15]
	v_mfma_f32_16x16x32_bf16 v[12:15], v[146:149], v[246:249], v[12:15]
	v_mfma_f32_16x16x32_bf16 v[28:31], v[146:149], v[242:245], v[28:31]
	v_mfma_f32_16x16x32_bf16 v[28:31], v[142:145], v[234:237], v[28:31]
	v_mfma_f32_16x16x32_bf16 v[44:47], v[142:145], v[222:225], v[44:47]
	v_mfma_f32_16x16x32_bf16 v[44:47], v[146:149], v[230:233], v[44:47]
	v_mfma_f32_16x16x32_bf16 v[60:63], v[146:149], v[226:229], v[60:63]
	v_mfma_f32_16x16x32_bf16 v[60:63], v[142:145], v[218:221], v[60:63]
	v_mfma_f32_16x16x32_bf16 v[56:59], v[150:153], v[218:221], v[56:59]
	v_mfma_f32_16x16x32_bf16 v[56:59], v[174:177], v[226:229], v[56:59]
	v_mfma_f32_16x16x32_bf16 v[40:43], v[174:177], v[230:233], v[40:43]
	v_mfma_f32_16x16x32_bf16 v[40:43], v[150:153], v[222:225], v[40:43]
	v_mfma_f32_16x16x32_bf16 v[24:27], v[150:153], v[234:237], v[24:27]
	v_mfma_f32_16x16x32_bf16 v[24:27], v[174:177], v[242:245], v[24:27]
	v_mfma_f32_16x16x32_bf16 v[8:11], v[174:177], v[246:249], v[8:11]
	v_mfma_f32_16x16x32_bf16 v[8:11], v[150:153], v[238:241], v[8:11]
	v_mfma_f32_16x16x32_bf16 v[4:7], v[178:181], v[238:241], v[4:7]
	v_mfma_f32_16x16x32_bf16 v[4:7], v[182:185], v[246:249], v[4:7]
	v_mfma_f32_16x16x32_bf16 v[20:23], v[182:185], v[242:245], v[20:23]
	v_mfma_f32_16x16x32_bf16 v[20:23], v[178:181], v[234:237], v[20:23]
	v_mfma_f32_16x16x32_bf16 v[36:39], v[178:181], v[222:225], v[36:39]
	v_mfma_f32_16x16x32_bf16 v[36:39], v[182:185], v[230:233], v[36:39]
	v_mfma_f32_16x16x32_bf16 v[52:55], v[182:185], v[226:229], v[52:55]
	v_mfma_f32_16x16x32_bf16 v[52:55], v[178:181], v[218:221], v[52:55]
	s_barrier
	ds_read_b128 v[134:137], v213
	ds_read_b128 v[138:141], v214
	ds_read_b128 v[142:145], v209
	ds_read_b128 v[146:149], v210
	ds_read_b128 v[150:153], v215
	ds_read_b128 v[174:177], v216
	ds_read_b128 v[178:181], v211
	ds_read_b128 v[182:185], v212
	s_mov_b32 m0, s79
	v_lshl_add_u64 v[250:251], s[82:83], 0, v[0:1]
	ds_read_b128 v[218:221], v207 offset:32768
	ds_read_b128 v[222:225], v207 offset:34816
	ds_read_b128 v[226:229], v208 offset:32768
	ds_read_b128 v[230:233], v208 offset:34816
	ds_read_b128 v[234:237], v207 offset:36864
	ds_read_b128 v[238:241], v207 offset:38912
	ds_read_b128 v[242:245], v208 offset:36864
	ds_read_b128 v[246:249], v208 offset:38912
	global_load_lds_dwordx4 v[250:251], off
	v_lshl_add_u64 v[252:253], v[250:251], 0, s[20:21]
	s_mov_b32 m0, s81
	s_nop 0
	global_load_lds_dwordx4 v[252:253], off
	v_lshl_add_u64 v[252:253], v[250:251], 0, s[14:15]
	s_mov_b32 m0, s97
	v_lshl_add_u64 v[250:251], v[250:251], 0, s[22:23]
	global_load_lds_dwordx4 v[252:253], off
	s_mov_b32 m0, s64
	s_nop 0
	global_load_lds_dwordx4 v[250:251], off
	s_waitcnt vmcnt(8)
	s_waitcnt lgkmcnt(0)
	s_barrier
	v_mfma_f32_16x16x32_bf16 v[128:131], v[134:137], v[218:221], v[128:131]
	v_mfma_f32_16x16x32_bf16 v[128:131], v[138:141], v[226:229], v[128:131]
	v_mfma_f32_16x16x32_bf16 v[112:115], v[138:141], v[230:233], v[112:115]
	v_mfma_f32_16x16x32_bf16 v[112:115], v[134:137], v[222:225], v[112:115]
	v_mfma_f32_16x16x32_bf16 v[96:99], v[134:137], v[234:237], v[96:99]
	v_mfma_f32_16x16x32_bf16 v[96:99], v[138:141], v[242:245], v[96:99]
	v_mfma_f32_16x16x32_bf16 v[80:83], v[138:141], v[246:249], v[80:83]
	v_mfma_f32_16x16x32_bf16 v[80:83], v[134:137], v[238:241], v[80:83]
	v_mfma_f32_16x16x32_bf16 v[76:79], v[142:145], v[238:241], v[76:79]
	v_mfma_f32_16x16x32_bf16 v[76:79], v[146:149], v[246:249], v[76:79]
	v_mfma_f32_16x16x32_bf16 v[92:95], v[146:149], v[242:245], v[92:95]
	v_mfma_f32_16x16x32_bf16 v[92:95], v[142:145], v[234:237], v[92:95]
	v_mfma_f32_16x16x32_bf16 v[108:111], v[142:145], v[222:225], v[108:111]
	v_mfma_f32_16x16x32_bf16 v[108:111], v[146:149], v[230:233], v[108:111]
	v_mfma_f32_16x16x32_bf16 v[124:127], v[146:149], v[226:229], v[124:127]
	v_mfma_f32_16x16x32_bf16 v[124:127], v[142:145], v[218:221], v[124:127]
	v_mfma_f32_16x16x32_bf16 v[120:123], v[150:153], v[218:221], v[120:123]
	v_mfma_f32_16x16x32_bf16 v[120:123], v[174:177], v[226:229], v[120:123]
	v_mfma_f32_16x16x32_bf16 v[104:107], v[174:177], v[230:233], v[104:107]
	v_mfma_f32_16x16x32_bf16 v[104:107], v[150:153], v[222:225], v[104:107]
	v_mfma_f32_16x16x32_bf16 v[88:91], v[150:153], v[234:237], v[88:91]
	v_mfma_f32_16x16x32_bf16 v[88:91], v[174:177], v[242:245], v[88:91]
	v_mfma_f32_16x16x32_bf16 v[72:75], v[174:177], v[246:249], v[72:75]
	v_mfma_f32_16x16x32_bf16 v[72:75], v[150:153], v[238:241], v[72:75]
	v_mfma_f32_16x16x32_bf16 v[68:71], v[178:181], v[238:241], v[68:71]
	v_mfma_f32_16x16x32_bf16 v[68:71], v[182:185], v[246:249], v[68:71]
	v_mfma_f32_16x16x32_bf16 v[84:87], v[182:185], v[242:245], v[84:87]
	v_mfma_f32_16x16x32_bf16 v[84:87], v[178:181], v[234:237], v[84:87]
	v_mfma_f32_16x16x32_bf16 v[100:103], v[178:181], v[222:225], v[100:103]
	v_mfma_f32_16x16x32_bf16 v[100:103], v[182:185], v[230:233], v[100:103]
	v_mfma_f32_16x16x32_bf16 v[116:119], v[182:185], v[226:229], v[116:119]
	v_mfma_f32_16x16x32_bf16 v[116:119], v[178:181], v[218:221], v[116:119]
	s_barrier
	s_add_i32 s24, s70, s77
	v_lshl_add_u64 v[250:251], v[154:155], 0, s[48:49]
	s_mov_b32 m0, s24
	ds_read_b128 v[218:221], v207 offset:49152
	ds_read_b128 v[222:225], v207 offset:51200
	ds_read_b128 v[226:229], v208 offset:49152
	ds_read_b128 v[230:233], v208 offset:51200
	ds_read_b128 v[234:237], v207 offset:53248
	ds_read_b128 v[238:241], v207 offset:55296
	ds_read_b128 v[242:245], v208 offset:53248
	ds_read_b128 v[246:249], v208 offset:55296
	global_load_lds_dwordx4 v[250:251], off
	v_lshl_add_u64 v[250:251], v[154:155], 0, s[50:51]
	s_add_i32 m0, s24, 0x2000
	s_add_i32 s24, s71, s77
	global_load_lds_dwordx4 v[250:251], off
	v_lshl_add_u64 v[250:251], v[154:155], 0, s[52:53]
	s_mov_b32 m0, s24
	v_lshl_add_u64 v[154:155], v[154:155], 0, s[54:55]
	global_load_lds_dwordx4 v[250:251], off
	s_add_i32 m0, s24, 0x2000
	s_nop 0
	global_load_lds_dwordx4 v[154:155], off
	s_waitcnt vmcnt(4)
	s_waitcnt lgkmcnt(0)
	s_barrier
	v_mfma_f32_16x16x32_bf16 v[64:67], v[134:137], v[218:221], v[64:67]
	v_mfma_f32_16x16x32_bf16 v[64:67], v[138:141], v[226:229], v[64:67]
	v_mfma_f32_16x16x32_bf16 v[48:51], v[138:141], v[230:233], v[48:51]
	v_mfma_f32_16x16x32_bf16 v[48:51], v[134:137], v[222:225], v[48:51]
	v_mfma_f32_16x16x32_bf16 v[32:35], v[134:137], v[234:237], v[32:35]
	v_mfma_f32_16x16x32_bf16 v[32:35], v[138:141], v[242:245], v[32:35]
	v_mfma_f32_16x16x32_bf16 v[16:19], v[138:141], v[246:249], v[16:19]
	v_mfma_f32_16x16x32_bf16 v[16:19], v[134:137], v[238:241], v[16:19]
	v_mfma_f32_16x16x32_bf16 v[12:15], v[142:145], v[238:241], v[12:15]
	v_mfma_f32_16x16x32_bf16 v[12:15], v[146:149], v[246:249], v[12:15]
	v_mfma_f32_16x16x32_bf16 v[28:31], v[146:149], v[242:245], v[28:31]
	v_mfma_f32_16x16x32_bf16 v[28:31], v[142:145], v[234:237], v[28:31]
	v_mfma_f32_16x16x32_bf16 v[44:47], v[142:145], v[222:225], v[44:47]
	v_mfma_f32_16x16x32_bf16 v[44:47], v[146:149], v[230:233], v[44:47]
	v_mfma_f32_16x16x32_bf16 v[60:63], v[146:149], v[226:229], v[60:63]
	v_mfma_f32_16x16x32_bf16 v[60:63], v[142:145], v[218:221], v[60:63]
	v_mfma_f32_16x16x32_bf16 v[56:59], v[150:153], v[218:221], v[56:59]
	v_mfma_f32_16x16x32_bf16 v[56:59], v[174:177], v[226:229], v[56:59]
	v_mfma_f32_16x16x32_bf16 v[40:43], v[174:177], v[230:233], v[40:43]
	v_mfma_f32_16x16x32_bf16 v[40:43], v[150:153], v[222:225], v[40:43]
	v_mfma_f32_16x16x32_bf16 v[24:27], v[150:153], v[234:237], v[24:27]
	v_mfma_f32_16x16x32_bf16 v[24:27], v[174:177], v[242:245], v[24:27]
	v_mfma_f32_16x16x32_bf16 v[8:11], v[174:177], v[246:249], v[8:11]
	v_mfma_f32_16x16x32_bf16 v[8:11], v[150:153], v[238:241], v[8:11]
	v_mfma_f32_16x16x32_bf16 v[4:7], v[178:181], v[238:241], v[4:7]
	v_mfma_f32_16x16x32_bf16 v[4:7], v[182:185], v[246:249], v[4:7]
	v_mfma_f32_16x16x32_bf16 v[20:23], v[182:185], v[242:245], v[20:23]
	v_mfma_f32_16x16x32_bf16 v[20:23], v[178:181], v[234:237], v[20:23]
	v_mfma_f32_16x16x32_bf16 v[36:39], v[178:181], v[222:225], v[36:39]
	v_mfma_f32_16x16x32_bf16 v[36:39], v[182:185], v[230:233], v[36:39]
	v_mfma_f32_16x16x32_bf16 v[52:55], v[182:185], v[226:229], v[52:55]
	v_mfma_f32_16x16x32_bf16 v[52:55], v[178:181], v[218:221], v[52:55]
	s_barrier
	s_add_i32 s94, s94, 2
	s_add_u32 vcc_lo, vcc_lo, 0x100
	s_addc_u32 vcc_hi, vcc_hi, 0
	s_cmp_gt_u32 s94, 13
	s_cbranch_scc0 .LBB0_384
	s_and_b64 vcc, exec, s[56:57]
	s_cbranch_vccz .LBB0_387
	s_barrier

.LBB0_779:
	v_add_u32_e32 v4, s73, v159
	v_add_u32_e32 v6, s73, v173
	ds_read_b128 v[136:139], v4
	ds_read_b128 v[140:143], v6
	v_add_u32_e32 v4, s77, v159
	s_add_u32 s26, s28, s64
	v_add_u32_e32 v6, s77, v173
	ds_read_b128 v[180:183], v4
	ds_read_b128 v[196:199], v6
	v_add_u32_e32 v4, s79, v159
	s_addc_u32 s27, s29, s65
	v_add_u32_e32 v6, s79, v173
	ds_read_b128 v[200:203], v4
	ds_read_b128 v[204:207], v6
	v_add_u32_e32 v4, s80, v159
	s_add_u32 s26, s26, 0x100
	v_add_u32_e32 v6, s80, v173
	ds_read_b128 v[208:211], v4
	ds_read_b128 v[212:215], v6
	s_addc_u32 s27, s27, 0
	s_add_u32 s34, s93, s64
	s_addc_u32 s35, s94, s65
	s_cmpk_eq_i32 s64, 0xb00
	s_cselect_b32 s35, s63, s35
	s_cselect_b32 s34, s62, s34
	s_cselect_b32 s27, s1, s27
	s_cselect_b32 s26, s0, s26
	v_lshl_add_u64 v[6:7], v[170:171], 0, s[64:65]
	v_lshl_add_u64 v[184:185], v[6:7], 0, s[24:25]
	s_add_i32 m0, s66, 0x8000
	s_mov_b64 s[38:39], 0x30080
	ds_read_b128 v[216:219], v176
	ds_read_b128 v[220:223], v176 offset:2048
	ds_read_b128 v[224:227], v177
	ds_read_b128 v[228:231], v177 offset:2048
	ds_read_b128 v[232:235], v176 offset:4096
	ds_read_b128 v[236:239], v176 offset:6144
	ds_read_b128 v[240:243], v177 offset:4096
	ds_read_b128 v[244:247], v177 offset:6144
	global_load_lds_dwordx4 v[184:185], off
	v_lshl_add_u64 v[184:185], v[6:7], 0, s[38:39]
	s_add_i32 m0, s66, 0xa000
	s_mov_b64 s[38:39], 0x90080
	global_load_lds_dwordx4 v[184:185], off
	v_lshl_add_u64 v[184:185], v[6:7], 0, s[50:51]
	s_add_i32 m0, s66, 0xc000
	v_lshl_add_u64 v[6:7], v[6:7], 0, s[38:39]
	global_load_lds_dwordx4 v[184:185], off
	s_add_i32 m0, s66, 0xe000
	s_nop 0
	global_load_lds_dwordx4 v[6:7], off
	s_waitcnt vmcnt(8)
	s_waitcnt lgkmcnt(0)
	s_barrier
	v_mfma_f32_16x16x32_bf16 v[132:135], v[136:139], v[216:219], v[132:135]
	v_mfma_f32_16x16x32_bf16 v[132:135], v[140:143], v[224:227], v[132:135]
	v_mfma_f32_16x16x32_bf16 v[116:119], v[140:143], v[228:231], v[116:119]
	v_mfma_f32_16x16x32_bf16 v[116:119], v[136:139], v[220:223], v[116:119]
	v_mfma_f32_16x16x32_bf16 v[100:103], v[136:139], v[232:235], v[100:103]
	v_mfma_f32_16x16x32_bf16 v[100:103], v[140:143], v[240:243], v[100:103]
	v_mfma_f32_16x16x32_bf16 v[84:87], v[140:143], v[244:247], v[84:87]
	v_mfma_f32_16x16x32_bf16 v[84:87], v[136:139], v[236:239], v[84:87]
	v_mfma_f32_16x16x32_bf16 v[80:83], v[180:183], v[236:239], v[80:83]
	v_mfma_f32_16x16x32_bf16 v[80:83], v[196:199], v[244:247], v[80:83]
	v_mfma_f32_16x16x32_bf16 v[96:99], v[196:199], v[240:243], v[96:99]
	v_mfma_f32_16x16x32_bf16 v[96:99], v[180:183], v[232:235], v[96:99]
	v_mfma_f32_16x16x32_bf16 v[112:115], v[180:183], v[220:223], v[112:115]
	v_mfma_f32_16x16x32_bf16 v[112:115], v[196:199], v[228:231], v[112:115]
	v_mfma_f32_16x16x32_bf16 v[128:131], v[196:199], v[224:227], v[128:131]
	v_mfma_f32_16x16x32_bf16 v[128:131], v[180:183], v[216:219], v[128:131]
	v_mfma_f32_16x16x32_bf16 v[124:127], v[200:203], v[216:219], v[124:127]
	v_mfma_f32_16x16x32_bf16 v[124:127], v[204:207], v[224:227], v[124:127]
	v_mfma_f32_16x16x32_bf16 v[108:111], v[204:207], v[228:231], v[108:111]
	v_mfma_f32_16x16x32_bf16 v[108:111], v[200:203], v[220:223], v[108:111]
	v_mfma_f32_16x16x32_bf16 v[92:95], v[200:203], v[232:235], v[92:95]
	v_mfma_f32_16x16x32_bf16 v[92:95], v[204:207], v[240:243], v[92:95]
	v_mfma_f32_16x16x32_bf16 v[76:79], v[204:207], v[244:247], v[76:79]
	v_mfma_f32_16x16x32_bf16 v[76:79], v[200:203], v[236:239], v[76:79]
	v_mfma_f32_16x16x32_bf16 v[72:75], v[208:211], v[236:239], v[72:75]
	v_mfma_f32_16x16x32_bf16 v[72:75], v[212:215], v[244:247], v[72:75]
	v_mfma_f32_16x16x32_bf16 v[88:91], v[212:215], v[240:243], v[88:91]
	v_mfma_f32_16x16x32_bf16 v[88:91], v[208:211], v[232:235], v[88:91]
	v_mfma_f32_16x16x32_bf16 v[104:107], v[208:211], v[220:223], v[104:107]
	v_mfma_f32_16x16x32_bf16 v[104:107], v[212:215], v[228:231], v[104:107]
	v_mfma_f32_16x16x32_bf16 v[120:123], v[212:215], v[224:227], v[120:123]
	v_mfma_f32_16x16x32_bf16 v[120:123], v[208:211], v[216:219], v[120:123]
	s_barrier
	v_lshl_add_u64 v[184:185], s[34:35], 0, v[146:147]
	s_add_i32 s34, s73, s3
	s_mov_b32 m0, s34
	ds_read_b128 v[216:219], v176 offset:16384
	ds_read_b128 v[220:223], v176 offset:18432
	ds_read_b128 v[224:227], v177 offset:16384
	ds_read_b128 v[228:231], v177 offset:18432
	ds_read_b128 v[232:235], v176 offset:20480
	ds_read_b128 v[236:239], v176 offset:22528
	ds_read_b128 v[240:243], v177 offset:20480
	ds_read_b128 v[244:247], v177 offset:22528
	global_load_lds_dwordx4 v[184:185], off
	v_lshl_add_u64 v[6:7], v[184:185], 0, s[12:13]
	s_add_i32 m0, s34, 0x2000
	s_add_i32 s34, s79, s3
	global_load_lds_dwordx4 v[6:7], off
	v_lshl_add_u64 v[6:7], v[184:185], 0, s[14:15]
	s_mov_b32 m0, s34
	s_nop 0
	global_load_lds_dwordx4 v[6:7], off
	v_lshl_add_u64 v[6:7], v[184:185], 0, s[16:17]
	s_add_i32 m0, s34, 0x2000
	s_nop 0
	global_load_lds_dwordx4 v[6:7], off
	s_waitcnt vmcnt(4)
	s_waitcnt lgkmcnt(0)
	s_barrier
	v_mfma_f32_16x16x32_bf16 v[68:71], v[136:139], v[216:219], v[68:71]
	v_mfma_f32_16x16x32_bf16 v[68:71], v[140:143], v[224:227], v[68:71]
	v_mfma_f32_16x16x32_bf16 v[52:55], v[140:143], v[228:231], v[52:55]
	v_mfma_f32_16x16x32_bf16 v[52:55], v[136:139], v[220:223], v[52:55]
	v_mfma_f32_16x16x32_bf16 v[36:39], v[136:139], v[232:235], v[36:39]
	v_mfma_f32_16x16x32_bf16 v[36:39], v[140:143], v[240:243], v[36:39]
	v_mfma_f32_16x16x32_bf16 v[20:23], v[140:143], v[244:247], v[20:23]
	v_mfma_f32_16x16x32_bf16 v[20:23], v[136:139], v[236:239], v[20:23]
	v_mfma_f32_16x16x32_bf16 v[16:19], v[180:183], v[236:239], v[16:19]
	v_mfma_f32_16x16x32_bf16 v[16:19], v[196:199], v[244:247], v[16:19]
	v_mfma_f32_16x16x32_bf16 v[32:35], v[196:199], v[240:243], v[32:35]
	v_mfma_f32_16x16x32_bf16 v[32:35], v[180:183], v[232:235], v[32:35]
	v_mfma_f32_16x16x32_bf16 v[48:51], v[180:183], v[220:223], v[48:51]
	v_mfma_f32_16x16x32_bf16 v[48:51], v[196:199], v[228:231], v[48:51]
	v_mfma_f32_16x16x32_bf16 v[64:67], v[196:199], v[224:227], v[64:67]
	v_mfma_f32_16x16x32_bf16 v[64:67], v[180:183], v[216:219], v[64:67]
	v_mfma_f32_16x16x32_bf16 v[60:63], v[200:203], v[216:219], v[60:63]
	v_mfma_f32_16x16x32_bf16 v[60:63], v[204:207], v[224:227], v[60:63]
	v_mfma_f32_16x16x32_bf16 v[56:59], v[208:211], v[216:219], v[56:59]
	v_mfma_f32_16x16x32_bf16 v[56:59], v[212:215], v[224:227], v[56:59]
	v_mfma_f32_16x16x32_bf16 v[44:47], v[200:203], v[220:223], v[44:47]
	v_mfma_f32_16x16x32_bf16 v[44:47], v[204:207], v[228:231], v[44:47]
	v_mfma_f32_16x16x32_bf16 v[40:43], v[208:211], v[220:223], v[40:43]
	v_mfma_f32_16x16x32_bf16 v[40:43], v[212:215], v[228:231], v[40:43]
	v_mfma_f32_16x16x32_bf16 v[28:31], v[200:203], v[232:235], v[28:31]
	v_mfma_f32_16x16x32_bf16 v[28:31], v[204:207], v[240:243], v[28:31]
	v_mfma_f32_16x16x32_bf16 v[24:27], v[208:211], v[232:235], v[24:27]
	v_mfma_f32_16x16x32_bf16 v[24:27], v[212:215], v[240:243], v[24:27]
	v_mfma_f32_16x16x32_bf16 v[12:15], v[200:203], v[236:239], v[12:15]
	v_mfma_f32_16x16x32_bf16 v[12:15], v[204:207], v[244:247], v[12:15]
	v_mfma_f32_16x16x32_bf16 v[6:9], v[208:211], v[236:239], v[8:11]
	v_mfma_f32_16x16x32_bf16 v[6:9], v[212:215], v[244:247], v[6:9]
	s_barrier
	v_add_u32_e32 v4, s83, v159
	v_add_u32_e32 v10, s83, v173
	ds_read_b128 v[136:139], v4
	ds_read_b128 v[140:143], v10
	v_add_u32_e32 v4, s81, v159
	v_add_u32_e32 v10, s81, v173
	ds_read_b128 v[180:183], v4
	ds_read_b128 v[196:199], v10
	v_add_u32_e32 v4, s84, v159
	v_add_u32_e32 v10, s84, v173
	ds_read_b128 v[200:203], v4
	ds_read_b128 v[204:207], v10
	v_add_u32_e32 v4, s82, v159
	v_add_u32_e32 v10, s82, v173
	ds_read_b128 v[208:211], v4
	ds_read_b128 v[212:215], v10
	s_mov_b32 m0, s66
	v_lshl_add_u64 v[10:11], s[26:27], 0, v[144:145]
	ds_read_b128 v[216:219], v176 offset:32768
	ds_read_b128 v[220:223], v176 offset:34816
	ds_read_b128 v[224:227], v177 offset:32768
	ds_read_b128 v[228:231], v177 offset:34816
	ds_read_b128 v[232:235], v176 offset:36864
	ds_read_b128 v[236:239], v176 offset:38912
	ds_read_b128 v[240:243], v177 offset:36864
	ds_read_b128 v[244:247], v177 offset:38912
	global_load_lds_dwordx4 v[10:11], off
	v_lshl_add_u64 v[248:249], v[10:11], 0, s[18:19]
	s_mov_b32 m0, s67
	s_nop 0
	global_load_lds_dwordx4 v[248:249], off
	v_lshl_add_u64 v[248:249], v[10:11], 0, s[12:13]
	s_mov_b32 m0, s68
	v_lshl_add_u64 v[10:11], v[10:11], 0, s[20:21]
	global_load_lds_dwordx4 v[248:249], off
	s_mov_b32 m0, s69
	s_nop 0
	global_load_lds_dwordx4 v[10:11], off
	s_waitcnt vmcnt(8)
	s_waitcnt lgkmcnt(0)
	s_barrier
	v_mfma_f32_16x16x32_bf16 v[132:135], v[136:139], v[216:219], v[132:135]
	v_mfma_f32_16x16x32_bf16 v[132:135], v[140:143], v[224:227], v[132:135]
	v_mfma_f32_16x16x32_bf16 v[116:119], v[140:143], v[228:231], v[116:119]
	v_mfma_f32_16x16x32_bf16 v[116:119], v[136:139], v[220:223], v[116:119]
	v_mfma_f32_16x16x32_bf16 v[100:103], v[136:139], v[232:235], v[100:103]
	v_mfma_f32_16x16x32_bf16 v[100:103], v[140:143], v[240:243], v[100:103]
	v_mfma_f32_16x16x32_bf16 v[84:87], v[140:143], v[244:247], v[84:87]
	v_mfma_f32_16x16x32_bf16 v[84:87], v[136:139], v[236:239], v[84:87]
	v_mfma_f32_16x16x32_bf16 v[80:83], v[180:183], v[236:239], v[80:83]
	v_mfma_f32_16x16x32_bf16 v[80:83], v[196:199], v[244:247], v[80:83]
	v_mfma_f32_16x16x32_bf16 v[96:99], v[196:199], v[240:243], v[96:99]
	v_mfma_f32_16x16x32_bf16 v[96:99], v[180:183], v[232:235], v[96:99]
	v_mfma_f32_16x16x32_bf16 v[112:115], v[180:183], v[220:223], v[112:115]
	v_mfma_f32_16x16x32_bf16 v[112:115], v[196:199], v[228:231], v[112:115]
	v_mfma_f32_16x16x32_bf16 v[128:131], v[196:199], v[224:227], v[128:131]
	v_mfma_f32_16x16x32_bf16 v[128:131], v[180:183], v[216:219], v[128:131]
	v_mfma_f32_16x16x32_bf16 v[124:127], v[200:203], v[216:219], v[124:127]
	v_mfma_f32_16x16x32_bf16 v[124:127], v[204:207], v[224:227], v[124:127]
	v_mfma_f32_16x16x32_bf16 v[108:111], v[204:207], v[228:231], v[108:111]
	v_mfma_f32_16x16x32_bf16 v[108:111], v[200:203], v[220:223], v[108:111]
	v_mfma_f32_16x16x32_bf16 v[92:95], v[200:203], v[232:235], v[92:95]
	v_mfma_f32_16x16x32_bf16 v[92:95], v[204:207], v[240:243], v[92:95]
	v_mfma_f32_16x16x32_bf16 v[76:79], v[204:207], v[244:247], v[76:79]
	v_mfma_f32_16x16x32_bf16 v[76:79], v[200:203], v[236:239], v[76:79]
	v_mfma_f32_16x16x32_bf16 v[72:75], v[208:211], v[236:239], v[72:75]
	v_mfma_f32_16x16x32_bf16 v[72:75], v[212:215], v[244:247], v[72:75]
	v_mfma_f32_16x16x32_bf16 v[88:91], v[212:215], v[240:243], v[88:91]
	v_mfma_f32_16x16x32_bf16 v[88:91], v[208:211], v[232:235], v[88:91]
	v_mfma_f32_16x16x32_bf16 v[104:107], v[208:211], v[220:223], v[104:107]
	v_mfma_f32_16x16x32_bf16 v[104:107], v[212:215], v[228:231], v[104:107]
	v_mfma_f32_16x16x32_bf16 v[120:123], v[212:215], v[224:227], v[120:123]
	v_mfma_f32_16x16x32_bf16 v[120:123], v[208:211], v[216:219], v[120:123]
	s_barrier
	s_add_i32 s26, s83, s3
	v_lshl_add_u64 v[10:11], v[184:185], 0, s[24:25]
	s_mov_b32 m0, s26
	ds_read_b128 v[216:219], v176 offset:49152
	ds_read_b128 v[220:223], v176 offset:51200
	ds_read_b128 v[224:227], v177 offset:49152
	ds_read_b128 v[228:231], v177 offset:51200
	ds_read_b128 v[232:235], v176 offset:53248
	ds_read_b128 v[236:239], v176 offset:55296
	ds_read_b128 v[240:243], v177 offset:53248
	ds_read_b128 v[244:247], v177 offset:55296
	global_load_lds_dwordx4 v[10:11], off
	v_lshl_add_u64 v[10:11], v[184:185], 0, s[50:51]
	s_add_i32 m0, s26, 0x2000
	s_add_i32 s26, s84, s3
	global_load_lds_dwordx4 v[10:11], off
	v_lshl_add_u64 v[10:11], v[184:185], 0, s[52:53]
	s_mov_b32 m0, s26
	s_nop 0
	global_load_lds_dwordx4 v[10:11], off
	v_lshl_add_u64 v[10:11], v[184:185], 0, s[54:55]
	s_add_i32 m0, s26, 0x2000
	s_nop 0
	global_load_lds_dwordx4 v[10:11], off
	s_waitcnt vmcnt(4)
	s_waitcnt lgkmcnt(0)
	s_barrier
	v_mfma_f32_16x16x32_bf16 v[68:71], v[136:139], v[216:219], v[68:71]
	v_mfma_f32_16x16x32_bf16 v[68:71], v[140:143], v[224:227], v[68:71]
	v_mfma_f32_16x16x32_bf16 v[52:55], v[140:143], v[228:231], v[52:55]
	v_mfma_f32_16x16x32_bf16 v[52:55], v[136:139], v[220:223], v[52:55]
	v_mfma_f32_16x16x32_bf16 v[36:39], v[136:139], v[232:235], v[36:39]
	v_mfma_f32_16x16x32_bf16 v[36:39], v[140:143], v[240:243], v[36:39]
	v_mfma_f32_16x16x32_bf16 v[20:23], v[140:143], v[244:247], v[20:23]
	v_mfma_f32_16x16x32_bf16 v[20:23], v[136:139], v[236:239], v[20:23]
	v_mfma_f32_16x16x32_bf16 v[16:19], v[180:183], v[236:239], v[16:19]
	v_mfma_f32_16x16x32_bf16 v[16:19], v[196:199], v[244:247], v[16:19]
	v_mfma_f32_16x16x32_bf16 v[32:35], v[196:199], v[240:243], v[32:35]
	v_mfma_f32_16x16x32_bf16 v[32:35], v[180:183], v[232:235], v[32:35]
	v_mfma_f32_16x16x32_bf16 v[48:51], v[180:183], v[220:223], v[48:51]
	v_mfma_f32_16x16x32_bf16 v[48:51], v[196:199], v[228:231], v[48:51]
	v_mfma_f32_16x16x32_bf16 v[64:67], v[196:199], v[224:227], v[64:67]
	v_mfma_f32_16x16x32_bf16 v[64:67], v[180:183], v[216:219], v[64:67]
	v_mfma_f32_16x16x32_bf16 v[60:63], v[200:203], v[216:219], v[60:63]
	v_mfma_f32_16x16x32_bf16 v[60:63], v[204:207], v[224:227], v[60:63]
	v_mfma_f32_16x16x32_bf16 v[56:59], v[208:211], v[216:219], v[56:59]
	v_mfma_f32_16x16x32_bf16 v[56:59], v[212:215], v[224:227], v[56:59]
	v_mfma_f32_16x16x32_bf16 v[44:47], v[200:203], v[220:223], v[44:47]
	v_mfma_f32_16x16x32_bf16 v[44:47], v[204:207], v[228:231], v[44:47]
	v_mfma_f32_16x16x32_bf16 v[40:43], v[208:211], v[220:223], v[40:43]
	v_mfma_f32_16x16x32_bf16 v[40:43], v[212:215], v[228:231], v[40:43]
	v_mfma_f32_16x16x32_bf16 v[28:31], v[200:203], v[232:235], v[28:31]
	v_mfma_f32_16x16x32_bf16 v[28:31], v[204:207], v[240:243], v[28:31]
	v_mfma_f32_16x16x32_bf16 v[24:27], v[208:211], v[232:235], v[24:27]
	v_mfma_f32_16x16x32_bf16 v[24:27], v[212:215], v[240:243], v[24:27]
	v_mfma_f32_16x16x32_bf16 v[10:13], v[200:203], v[236:239], v[12:15]
	v_mfma_f32_16x16x32_bf16 v[12:15], v[204:207], v[244:247], v[10:13]
	v_mfma_f32_16x16x32_bf16 v[6:9], v[208:211], v[236:239], v[6:9]
	v_mfma_f32_16x16x32_bf16 v[8:11], v[212:215], v[244:247], v[6:9]
	s_barrier
	s_add_i32 s95, s95, 2
	s_add_u32 s64, s64, 0x100
	s_addc_u32 s65, s65, 0
	s_cmp_gt_u32 s95, 21
	s_cbranch_scc1 .LBB0_782

.LBB0_973:
	v_add_u32_e32 v133, s72, v163
	v_add_u32_e32 v140, s72, v164
	ds_read_b128 v[136:139], v133
	ds_read_b128 v[148:151], v140
	v_add_u32_e32 v133, s73, v163
	s_add_u32 s70, s28, s26
	v_add_u32_e32 v140, s73, v164
	s_waitcnt lgkmcnt(0)
	ds_read_b128 v[152:155], v133
	ds_read_b128 v[174:177], v140
	v_add_u32_e32 v133, s77, v163
	s_addc_u32 s71, s29, s27
	v_add_u32_e32 v140, s77, v164
	ds_read_b128 v[178:181], v133
	ds_read_b128 v[182:185], v140
	v_add_u32_e32 v133, s79, v163
	s_add_u32 s70, s70, 0x100
	v_add_u32_e32 v140, s79, v164
	ds_read_b128 v[196:199], v133
	ds_read_b128 v[200:203], v140
	s_addc_u32 s71, s71, 0
	s_add_u32 s86, s65, s26
	s_addc_u32 s87, s85, s27
	s_cmpk_eq_i32 s26, 0x700
	s_cselect_b32 s87, s61, s87
	s_cselect_b32 s86, s88, s86
	s_cselect_b32 s71, s54, s71
	s_cselect_b32 s70, s63, s70
	v_lshl_add_u64 v[140:141], v[134:135], 0, s[26:27]
	v_lshl_add_u64 v[160:161], v[140:141], 0, s[36:37]
	s_add_i32 m0, s5, 0x8000
	s_mov_b64 s[90:91], 0x20080
	ds_read_b128 v[204:207], v166
	ds_read_b128 v[208:211], v166 offset:2048
	ds_read_b128 v[212:215], v167
	ds_read_b128 v[216:219], v167 offset:2048
	ds_read_b128 v[220:223], v166 offset:4096
	ds_read_b128 v[224:227], v166 offset:6144
	ds_read_b128 v[228:231], v167 offset:4096
	ds_read_b128 v[232:235], v167 offset:6144
	global_load_lds_dwordx4 v[160:161], off
	v_lshl_add_u64 v[160:161], v[140:141], 0, s[90:91]
	s_add_i32 m0, s5, 0xa000
	s_mov_b64 s[90:91], 0x60080
	global_load_lds_dwordx4 v[160:161], off
	v_lshl_add_u64 v[160:161], v[140:141], 0, s[44:45]
	s_add_i32 m0, s5, 0xc000
	v_lshl_add_u64 v[140:141], v[140:141], 0, s[90:91]
	global_load_lds_dwordx4 v[160:161], off
	s_add_i32 m0, s5, 0xe000
	s_nop 0
	global_load_lds_dwordx4 v[140:141], off
	s_waitcnt vmcnt(8)
	s_waitcnt lgkmcnt(0)
	s_barrier
	v_mfma_f32_16x16x32_bf16 v[8:11], v[136:139], v[204:207], v[8:11]
	v_mfma_f32_16x16x32_bf16 v[8:11], v[148:151], v[212:215], v[8:11]
	v_mfma_f32_16x16x32_bf16 v[12:15], v[148:151], v[216:219], v[12:15]
	v_mfma_f32_16x16x32_bf16 v[12:15], v[136:139], v[208:211], v[12:15]
	v_mfma_f32_16x16x32_bf16 v[44:47], v[136:139], v[220:223], v[44:47]
	v_mfma_f32_16x16x32_bf16 v[44:47], v[148:151], v[228:231], v[44:47]
	v_mfma_f32_16x16x32_bf16 v[20:23], v[148:151], v[232:235], v[20:23]
	v_mfma_f32_16x16x32_bf16 v[20:23], v[136:139], v[224:227], v[20:23]
	v_mfma_f32_16x16x32_bf16 v[24:27], v[152:155], v[224:227], v[24:27]
	v_mfma_f32_16x16x32_bf16 v[24:27], v[174:177], v[232:235], v[24:27]
	v_mfma_f32_16x16x32_bf16 v[36:39], v[174:177], v[228:231], v[36:39]
	v_mfma_f32_16x16x32_bf16 v[36:39], v[152:155], v[220:223], v[36:39]
	v_mfma_f32_16x16x32_bf16 v[16:19], v[152:155], v[208:211], v[16:19]
	v_mfma_f32_16x16x32_bf16 v[16:19], v[174:177], v[216:219], v[16:19]
	v_mfma_f32_16x16x32_bf16 v[4:7], v[174:177], v[212:215], v[4:7]
	v_mfma_f32_16x16x32_bf16 v[4:7], v[152:155], v[204:207], v[4:7]
	v_mfma_f32_16x16x32_bf16 v[32:35], v[178:181], v[204:207], v[32:35]
	v_mfma_f32_16x16x32_bf16 v[32:35], v[182:185], v[212:215], v[32:35]
	v_mfma_f32_16x16x32_bf16 v[40:43], v[182:185], v[216:219], v[40:43]
	v_mfma_f32_16x16x32_bf16 v[40:43], v[178:181], v[208:211], v[40:43]
	v_mfma_f32_16x16x32_bf16 v[48:51], v[178:181], v[220:223], v[48:51]
	v_mfma_f32_16x16x32_bf16 v[48:51], v[182:185], v[228:231], v[48:51]
	v_mfma_f32_16x16x32_bf16 v[56:59], v[182:185], v[232:235], v[56:59]
	v_mfma_f32_16x16x32_bf16 v[56:59], v[178:181], v[224:227], v[56:59]
	v_mfma_f32_16x16x32_bf16 v[64:67], v[196:199], v[224:227], v[64:67]
	v_mfma_f32_16x16x32_bf16 v[64:67], v[200:203], v[232:235], v[64:67]
	v_mfma_f32_16x16x32_bf16 v[60:63], v[200:203], v[228:231], v[60:63]
	v_mfma_f32_16x16x32_bf16 v[60:63], v[196:199], v[220:223], v[60:63]
	v_mfma_f32_16x16x32_bf16 v[52:55], v[196:199], v[208:211], v[52:55]
	v_mfma_f32_16x16x32_bf16 v[52:55], v[200:203], v[216:219], v[52:55]
	v_mfma_f32_16x16x32_bf16 v[28:31], v[200:203], v[212:215], v[28:31]
	v_mfma_f32_16x16x32_bf16 v[28:31], v[196:199], v[204:207], v[28:31]
	s_barrier
	v_lshl_add_u64 v[140:141], s[86:87], 0, v[158:159]
	s_add_i32 s86, s72, s34
	s_mov_b32 m0, s86
	ds_read_b128 v[204:207], v166 offset:16384
	ds_read_b128 v[208:211], v166 offset:18432
	ds_read_b128 v[212:215], v167 offset:16384
	ds_read_b128 v[216:219], v167 offset:18432
	ds_read_b128 v[220:223], v166 offset:20480
	ds_read_b128 v[224:227], v166 offset:22528
	ds_read_b128 v[228:231], v167 offset:20480
	ds_read_b128 v[232:235], v167 offset:22528
	global_load_lds_dwordx4 v[140:141], off
	v_lshl_add_u64 v[160:161], v[140:141], 0, s[18:19]
	s_add_i32 m0, s86, 0x2000
	s_mov_b64 s[86:87], 0x10000
	global_load_lds_dwordx4 v[160:161], off
	v_lshl_add_u64 v[160:161], v[140:141], 0, s[86:87]
	s_add_i32 s86, s77, s34
	s_mov_b32 m0, s86
	s_nop 0
	global_load_lds_dwordx4 v[160:161], off
	v_lshl_add_u64 v[160:161], v[140:141], 0, s[20:21]
	s_add_i32 m0, s86, 0x2000
	s_nop 0
	global_load_lds_dwordx4 v[160:161], off
	s_waitcnt vmcnt(4)
	s_waitcnt lgkmcnt(0)
	s_barrier
	v_mfma_f32_16x16x32_bf16 v[68:71], v[136:139], v[204:207], v[68:71]
	v_mfma_f32_16x16x32_bf16 v[68:71], v[148:151], v[212:215], v[68:71]
	v_mfma_f32_16x16x32_bf16 v[92:95], v[148:151], v[216:219], v[92:95]
	v_mfma_f32_16x16x32_bf16 v[92:95], v[136:139], v[208:211], v[92:95]
	v_mfma_f32_16x16x32_bf16 v[76:79], v[136:139], v[220:223], v[76:79]
	v_mfma_f32_16x16x32_bf16 v[76:79], v[148:151], v[228:231], v[76:79]
	v_mfma_f32_16x16x32_bf16 v[116:119], v[148:151], v[232:235], v[116:119]
	v_mfma_f32_16x16x32_bf16 v[116:119], v[136:139], v[224:227], v[116:119]
	v_mfma_f32_16x16x32_bf16 v[108:111], v[152:155], v[224:227], v[108:111]
	v_mfma_f32_16x16x32_bf16 v[108:111], v[174:177], v[232:235], v[108:111]
	v_mfma_f32_16x16x32_bf16 v[80:83], v[174:177], v[228:231], v[80:83]
	v_mfma_f32_16x16x32_bf16 v[80:83], v[152:155], v[220:223], v[80:83]
	v_mfma_f32_16x16x32_bf16 v[84:87], v[152:155], v[208:211], v[84:87]
	v_mfma_f32_16x16x32_bf16 v[84:87], v[174:177], v[216:219], v[84:87]
	v_mfma_f32_16x16x32_bf16 v[72:75], v[174:177], v[212:215], v[72:75]
	v_mfma_f32_16x16x32_bf16 v[72:75], v[152:155], v[204:207], v[72:75]
	v_mfma_f32_16x16x32_bf16 v[88:91], v[178:181], v[204:207], v[88:91]
	v_mfma_f32_16x16x32_bf16 v[88:91], v[182:185], v[212:215], v[88:91]
	v_mfma_f32_16x16x32_bf16 v[96:99], v[182:185], v[216:219], v[96:99]
	v_mfma_f32_16x16x32_bf16 v[96:99], v[178:181], v[208:211], v[96:99]
	v_mfma_f32_16x16x32_bf16 v[112:115], v[178:181], v[220:223], v[112:115]
	v_mfma_f32_16x16x32_bf16 v[112:115], v[182:185], v[228:231], v[112:115]
	v_mfma_f32_16x16x32_bf16 v[120:123], v[182:185], v[232:235], v[120:123]
	v_mfma_f32_16x16x32_bf16 v[120:123], v[178:181], v[224:227], v[120:123]
	v_mfma_f32_16x16x32_bf16 v[128:131], v[196:199], v[224:227], v[128:131]
	v_mfma_f32_16x16x32_bf16 v[128:131], v[200:203], v[232:235], v[128:131]
	v_mfma_f32_16x16x32_bf16 v[124:127], v[200:203], v[228:231], v[124:127]
	v_mfma_f32_16x16x32_bf16 v[124:127], v[196:199], v[220:223], v[124:127]
	v_mfma_f32_16x16x32_bf16 v[104:107], v[196:199], v[208:211], v[104:107]
	v_mfma_f32_16x16x32_bf16 v[104:107], v[200:203], v[216:219], v[104:107]
	v_mfma_f32_16x16x32_bf16 v[100:103], v[200:203], v[212:215], v[100:103]
	v_mfma_f32_16x16x32_bf16 v[100:103], v[196:199], v[204:207], v[100:103]
	s_barrier
	v_add_u32_e32 v133, s82, v163
	v_add_u32_e32 v148, s82, v164
	ds_read_b128 v[136:139], v133
	ds_read_b128 v[148:151], v148
	v_add_u32_e32 v133, s80, v163
	v_add_u32_e32 v160, s80, v164
	ds_read_b128 v[152:155], v133
	ds_read_b128 v[174:177], v160
	v_add_u32_e32 v133, s83, v163
	v_add_u32_e32 v160, s83, v164
	ds_read_b128 v[178:181], v133
	ds_read_b128 v[182:185], v160
	v_add_u32_e32 v133, s81, v163
	v_add_u32_e32 v160, s81, v164
	ds_read_b128 v[196:199], v133
	ds_read_b128 v[200:203], v160
	s_mov_b32 m0, s5
	v_lshl_add_u64 v[160:161], s[70:71], 0, v[0:1]
	s_mov_b64 s[70:71], 0x20000
	ds_read_b128 v[204:207], v166 offset:32768
	ds_read_b128 v[208:211], v166 offset:34816
	ds_read_b128 v[212:215], v167 offset:32768
	ds_read_b128 v[216:219], v167 offset:34816
	ds_read_b128 v[220:223], v166 offset:36864
	ds_read_b128 v[224:227], v166 offset:38912
	ds_read_b128 v[228:231], v167 offset:36864
	ds_read_b128 v[232:235], v167 offset:38912
	global_load_lds_dwordx4 v[160:161], off
	v_lshl_add_u64 v[170:171], v[160:161], 0, s[70:71]
	s_mov_b32 m0, s17
	s_nop 0
	global_load_lds_dwordx4 v[170:171], off
	v_lshl_add_u64 v[170:171], v[160:161], 0, s[18:19]
	s_mov_b32 m0, s35
	v_lshl_add_u64 v[160:161], v[160:161], 0, s[22:23]
	global_load_lds_dwordx4 v[170:171], off
	s_mov_b32 m0, s38
	s_nop 0
	global_load_lds_dwordx4 v[160:161], off
	s_waitcnt vmcnt(8)
	s_waitcnt lgkmcnt(0)
	s_barrier
	v_mfma_f32_16x16x32_bf16 v[8:11], v[136:139], v[204:207], v[8:11]
	v_mfma_f32_16x16x32_bf16 v[8:11], v[148:151], v[212:215], v[8:11]
	v_mfma_f32_16x16x32_bf16 v[12:15], v[148:151], v[216:219], v[12:15]
	v_mfma_f32_16x16x32_bf16 v[12:15], v[136:139], v[208:211], v[12:15]
	v_mfma_f32_16x16x32_bf16 v[44:47], v[136:139], v[220:223], v[44:47]
	v_mfma_f32_16x16x32_bf16 v[44:47], v[148:151], v[228:231], v[44:47]
	v_mfma_f32_16x16x32_bf16 v[20:23], v[148:151], v[232:235], v[20:23]
	v_mfma_f32_16x16x32_bf16 v[20:23], v[136:139], v[224:227], v[20:23]
	v_mfma_f32_16x16x32_bf16 v[24:27], v[152:155], v[224:227], v[24:27]
	v_mfma_f32_16x16x32_bf16 v[24:27], v[174:177], v[232:235], v[24:27]
	v_mfma_f32_16x16x32_bf16 v[36:39], v[174:177], v[228:231], v[36:39]
	v_mfma_f32_16x16x32_bf16 v[36:39], v[152:155], v[220:223], v[36:39]
	v_mfma_f32_16x16x32_bf16 v[16:19], v[152:155], v[208:211], v[16:19]
	v_mfma_f32_16x16x32_bf16 v[16:19], v[174:177], v[216:219], v[16:19]
	v_mfma_f32_16x16x32_bf16 v[4:7], v[174:177], v[212:215], v[4:7]
	v_mfma_f32_16x16x32_bf16 v[4:7], v[152:155], v[204:207], v[4:7]
	v_mfma_f32_16x16x32_bf16 v[32:35], v[178:181], v[204:207], v[32:35]
	v_mfma_f32_16x16x32_bf16 v[32:35], v[182:185], v[212:215], v[32:35]
	v_mfma_f32_16x16x32_bf16 v[40:43], v[182:185], v[216:219], v[40:43]
	v_mfma_f32_16x16x32_bf16 v[40:43], v[178:181], v[208:211], v[40:43]
	v_mfma_f32_16x16x32_bf16 v[48:51], v[178:181], v[220:223], v[48:51]
	v_mfma_f32_16x16x32_bf16 v[48:51], v[182:185], v[228:231], v[48:51]
	v_mfma_f32_16x16x32_bf16 v[56:59], v[182:185], v[232:235], v[56:59]
	v_mfma_f32_16x16x32_bf16 v[56:59], v[178:181], v[224:227], v[56:59]
	v_mfma_f32_16x16x32_bf16 v[64:67], v[196:199], v[224:227], v[64:67]
	v_mfma_f32_16x16x32_bf16 v[64:67], v[200:203], v[232:235], v[64:67]
	v_mfma_f32_16x16x32_bf16 v[60:63], v[200:203], v[228:231], v[60:63]
	v_mfma_f32_16x16x32_bf16 v[60:63], v[196:199], v[220:223], v[60:63]
	v_mfma_f32_16x16x32_bf16 v[52:55], v[196:199], v[208:211], v[52:55]
	v_mfma_f32_16x16x32_bf16 v[52:55], v[200:203], v[216:219], v[52:55]
	v_mfma_f32_16x16x32_bf16 v[28:31], v[200:203], v[212:215], v[28:31]
	v_mfma_f32_16x16x32_bf16 v[28:31], v[196:199], v[204:207], v[28:31]
	s_barrier
	s_add_i32 s70, s82, s34
	v_lshl_add_u64 v[160:161], v[140:141], 0, s[36:37]
	s_mov_b32 m0, s70
	ds_read_b128 v[204:207], v166 offset:49152
	ds_read_b128 v[208:211], v166 offset:51200
	ds_read_b128 v[212:215], v167 offset:49152
	ds_read_b128 v[216:219], v167 offset:51200
	ds_read_b128 v[220:223], v166 offset:53248
	ds_read_b128 v[224:227], v166 offset:55296
	ds_read_b128 v[228:231], v167 offset:53248
	ds_read_b128 v[232:235], v167 offset:55296
	global_load_lds_dwordx4 v[160:161], off
	v_lshl_add_u64 v[160:161], v[140:141], 0, s[44:45]
	s_add_i32 m0, s70, 0x2000
	s_add_i32 s70, s83, s34
	global_load_lds_dwordx4 v[160:161], off
	v_lshl_add_u64 v[160:161], v[140:141], 0, s[46:47]
	s_mov_b32 m0, s70
	v_lshl_add_u64 v[140:141], v[140:141], 0, s[50:51]
	global_load_lds_dwordx4 v[160:161], off
	s_add_i32 m0, s70, 0x2000
	s_nop 0
	global_load_lds_dwordx4 v[140:141], off
	s_waitcnt vmcnt(4)
	s_waitcnt lgkmcnt(0)
	s_barrier
	v_mfma_f32_16x16x32_bf16 v[68:71], v[136:139], v[204:207], v[68:71]
	v_mfma_f32_16x16x32_bf16 v[68:71], v[148:151], v[212:215], v[68:71]
	v_mfma_f32_16x16x32_bf16 v[92:95], v[148:151], v[216:219], v[92:95]
	v_mfma_f32_16x16x32_bf16 v[92:95], v[136:139], v[208:211], v[92:95]
	v_mfma_f32_16x16x32_bf16 v[76:79], v[136:139], v[220:223], v[76:79]
	v_mfma_f32_16x16x32_bf16 v[76:79], v[148:151], v[228:231], v[76:79]
	v_mfma_f32_16x16x32_bf16 v[116:119], v[148:151], v[232:235], v[116:119]
	v_mfma_f32_16x16x32_bf16 v[116:119], v[136:139], v[224:227], v[116:119]
	v_mfma_f32_16x16x32_bf16 v[108:111], v[152:155], v[224:227], v[108:111]
	v_mfma_f32_16x16x32_bf16 v[108:111], v[174:177], v[232:235], v[108:111]
	v_mfma_f32_16x16x32_bf16 v[80:83], v[174:177], v[228:231], v[80:83]
	v_mfma_f32_16x16x32_bf16 v[80:83], v[152:155], v[220:223], v[80:83]
	v_mfma_f32_16x16x32_bf16 v[84:87], v[152:155], v[208:211], v[84:87]
	v_mfma_f32_16x16x32_bf16 v[84:87], v[174:177], v[216:219], v[84:87]
	v_mfma_f32_16x16x32_bf16 v[72:75], v[174:177], v[212:215], v[72:75]
	v_mfma_f32_16x16x32_bf16 v[72:75], v[152:155], v[204:207], v[72:75]
	v_mfma_f32_16x16x32_bf16 v[88:91], v[178:181], v[204:207], v[88:91]
	v_mfma_f32_16x16x32_bf16 v[88:91], v[182:185], v[212:215], v[88:91]
	v_mfma_f32_16x16x32_bf16 v[96:99], v[182:185], v[216:219], v[96:99]
	v_mfma_f32_16x16x32_bf16 v[96:99], v[178:181], v[208:211], v[96:99]
	v_mfma_f32_16x16x32_bf16 v[112:115], v[178:181], v[220:223], v[112:115]
	v_mfma_f32_16x16x32_bf16 v[112:115], v[182:185], v[228:231], v[112:115]
	v_mfma_f32_16x16x32_bf16 v[120:123], v[182:185], v[232:235], v[120:123]
	v_mfma_f32_16x16x32_bf16 v[120:123], v[178:181], v[224:227], v[120:123]
	v_mfma_f32_16x16x32_bf16 v[128:131], v[196:199], v[224:227], v[128:131]
	v_mfma_f32_16x16x32_bf16 v[128:131], v[200:203], v[232:235], v[128:131]
	v_mfma_f32_16x16x32_bf16 v[124:127], v[200:203], v[228:231], v[124:127]
	v_mfma_f32_16x16x32_bf16 v[124:127], v[196:199], v[220:223], v[124:127]
	v_mfma_f32_16x16x32_bf16 v[104:107], v[196:199], v[208:211], v[104:107]
	v_mfma_f32_16x16x32_bf16 v[104:107], v[200:203], v[216:219], v[104:107]
	v_mfma_f32_16x16x32_bf16 v[100:103], v[200:203], v[212:215], v[100:103]
	v_mfma_f32_16x16x32_bf16 v[100:103], v[196:199], v[204:207], v[100:103]
	s_barrier
	s_add_i32 s89, s89, 2
	s_add_u32 s26, s26, 0x100
	s_addc_u32 s27, s27, 0
	s_cmp_gt_u32 s89, 13
	s_cbranch_scc0 .LBB0_973
	s_and_b64 vcc, exec, s[52:53]
	s_cbranch_vccz .LBB0_976
	s_barrier

.LBB0_1134:
	s_ashr_i32 s57, s56, 31
	s_lshl_b64 s[60:61], s[56:57], 19
	s_add_u32 s60, s42, s60
	s_addc_u32 s61, s43, s61
	s_and_b64 s[62:63], s[10:11], exec
	s_cselect_b32 s57, s61, s27
	s_cselect_b32 s79, s60, s26
	s_ashr_i32 s59, s58, 31
	s_lshl_b64 s[62:63], s[58:59], 19
	v_readlane_b32 s70, v254, 7
	v_readlane_b32 s71, v254, 8
	s_add_u32 s62, s70, s62
	s_addc_u32 s63, s71, s63
	s_and_b64 s[70:71], s[10:11], exec
	s_cselect_b32 s59, s63, s69
	s_cselect_b32 s80, s62, s68
	s_add_u32 s81, s68, 0x100
	v_lshl_add_u64 v[138:139], s[26:27], 0, v[132:133]
	s_addc_u32 s82, s69, 0
	s_mov_b32 s83, -2
	s_mov_b64 s[68:69], 0
	ds_read_b128 v[168:171], v145
	ds_read_b128 v[174:177], v146
	ds_read_b128 v[178:181], v147
	ds_read_b128 v[182:185], v148
	ds_read_b128 v[194:197], v149
	ds_read_b128 v[198:201], v150
	ds_read_b128 v[202:205], v151
	ds_read_b128 v[206:209], v152
	s_add_u32 s70, s26, s68
	s_addc_u32 s71, s27, s69
	s_add_u32 s70, s70, 0x100
	s_addc_u32 s71, s71, 0
	s_add_u32 s84, s81, s68
	s_addc_u32 s85, s82, s69
	s_cmpk_eq_i32 s68, 0x700
	s_cselect_b32 s85, s59, s85
	s_cselect_b32 s84, s80, s84
	s_cselect_b32 s71, s57, s71
	s_cselect_b32 s70, s79, s70
	v_lshl_add_u64 v[140:141], v[138:139], 0, s[68:69]
	v_lshl_add_u64 v[242:243], v[140:141], 0, s[22:23]
	s_add_i32 m0, s34, 0x8000
	s_mov_b64 s[86:87], 0x20080
	ds_read_b128 v[210:213], v153
	ds_read_b128 v[214:217], v153 offset:2048
	ds_read_b128 v[218:221], v154
	ds_read_b128 v[222:225], v154 offset:2048
	ds_read_b128 v[226:229], v153 offset:4096
	ds_read_b128 v[230:233], v153 offset:6144
	ds_read_b128 v[234:237], v154 offset:4096
	ds_read_b128 v[238:241], v154 offset:6144
	global_load_lds_dwordx4 v[242:243], off
	v_lshl_add_u64 v[242:243], v[140:141], 0, s[86:87]
	s_add_i32 m0, s34, 0xa000
	s_mov_b64 s[86:87], 0x60080
	global_load_lds_dwordx4 v[242:243], off
	v_lshl_add_u64 v[242:243], v[140:141], 0, s[24:25]
	s_add_i32 m0, s34, 0xc000
	v_lshl_add_u64 v[140:141], v[140:141], 0, s[86:87]
	global_load_lds_dwordx4 v[242:243], off
	s_add_i32 m0, s34, 0xe000
	s_nop 0
	global_load_lds_dwordx4 v[140:141], off
	s_waitcnt lgkmcnt(0)
	s_barrier
	v_mfma_f32_16x16x32_bf16 v[128:131], v[168:171], v[210:213], 0
	v_mfma_f32_16x16x32_bf16 v[128:131], v[174:177], v[218:221], v[128:131]
	v_mfma_f32_16x16x32_bf16 v[112:115], v[168:171], v[214:217], 0
	v_mfma_f32_16x16x32_bf16 v[112:115], v[174:177], v[222:225], v[112:115]
	v_mfma_f32_16x16x32_bf16 v[96:99], v[168:171], v[226:229], 0
	v_mfma_f32_16x16x32_bf16 v[96:99], v[174:177], v[234:237], v[96:99]
	v_mfma_f32_16x16x32_bf16 v[80:83], v[168:171], v[230:233], 0
	v_mfma_f32_16x16x32_bf16 v[80:83], v[174:177], v[238:241], v[80:83]
	v_mfma_f32_16x16x32_bf16 v[76:79], v[178:181], v[230:233], 0
	v_mfma_f32_16x16x32_bf16 v[76:79], v[182:185], v[238:241], v[76:79]
	v_mfma_f32_16x16x32_bf16 v[92:95], v[178:181], v[226:229], 0
	v_mfma_f32_16x16x32_bf16 v[92:95], v[182:185], v[234:237], v[92:95]
	v_mfma_f32_16x16x32_bf16 v[108:111], v[178:181], v[214:217], 0
	v_mfma_f32_16x16x32_bf16 v[108:111], v[182:185], v[222:225], v[108:111]
	v_mfma_f32_16x16x32_bf16 v[124:127], v[178:181], v[210:213], 0
	v_mfma_f32_16x16x32_bf16 v[124:127], v[182:185], v[218:221], v[124:127]
	v_mfma_f32_16x16x32_bf16 v[120:123], v[194:197], v[210:213], 0
	v_mfma_f32_16x16x32_bf16 v[120:123], v[198:201], v[218:221], v[120:123]
	v_mfma_f32_16x16x32_bf16 v[104:107], v[194:197], v[214:217], 0
	v_mfma_f32_16x16x32_bf16 v[104:107], v[198:201], v[222:225], v[104:107]
	v_mfma_f32_16x16x32_bf16 v[88:91], v[194:197], v[226:229], 0
	v_mfma_f32_16x16x32_bf16 v[88:91], v[198:201], v[234:237], v[88:91]
	v_mfma_f32_16x16x32_bf16 v[72:75], v[194:197], v[230:233], 0
	v_mfma_f32_16x16x32_bf16 v[72:75], v[198:201], v[238:241], v[72:75]
	v_mfma_f32_16x16x32_bf16 v[68:71], v[202:205], v[230:233], 0
	v_mfma_f32_16x16x32_bf16 v[68:71], v[206:209], v[238:241], v[68:71]
	v_mfma_f32_16x16x32_bf16 v[84:87], v[202:205], v[226:229], 0
	v_mfma_f32_16x16x32_bf16 v[84:87], v[206:209], v[234:237], v[84:87]
	v_mfma_f32_16x16x32_bf16 v[100:103], v[202:205], v[214:217], 0
	v_mfma_f32_16x16x32_bf16 v[100:103], v[206:209], v[222:225], v[100:103]
	v_mfma_f32_16x16x32_bf16 v[116:119], v[202:205], v[210:213], 0
	v_mfma_f32_16x16x32_bf16 v[116:119], v[206:209], v[218:221], v[116:119]
	s_barrier
	v_lshl_add_u64 v[140:141], s[84:85], 0, v[158:159]
	s_add_i32 s84, s67, s3
	s_mov_b32 m0, s84
	ds_read_b128 v[210:213], v153 offset:16384
	ds_read_b128 v[214:217], v153 offset:18432
	ds_read_b128 v[218:221], v154 offset:16384
	ds_read_b128 v[222:225], v154 offset:18432
	ds_read_b128 v[226:229], v153 offset:20480
	ds_read_b128 v[230:233], v153 offset:22528
	ds_read_b128 v[234:237], v154 offset:20480
	ds_read_b128 v[238:241], v154 offset:22528
	global_load_lds_dwordx4 v[140:141], off
	v_lshl_add_u64 v[242:243], v[140:141], 0, s[0:1]
	s_add_i32 m0, s84, 0x2000
	s_add_i32 s84, s72, s3
	global_load_lds_dwordx4 v[242:243], off
	v_lshl_add_u64 v[242:243], v[140:141], 0, s[12:13]
	s_mov_b32 m0, s84
	s_nop 0
	global_load_lds_dwordx4 v[242:243], off
	v_lshl_add_u64 v[242:243], v[140:141], 0, s[14:15]
	s_add_i32 m0, s84, 0x2000
	s_nop 0
	global_load_lds_dwordx4 v[242:243], off
	s_waitcnt vmcnt(4)
	s_waitcnt lgkmcnt(0)
	s_barrier
	v_mfma_f32_16x16x32_bf16 v[64:67], v[168:171], v[210:213], 0
	v_mfma_f32_16x16x32_bf16 v[64:67], v[174:177], v[218:221], v[64:67]
	v_mfma_f32_16x16x32_bf16 v[48:51], v[168:171], v[214:217], 0
	v_mfma_f32_16x16x32_bf16 v[48:51], v[174:177], v[222:225], v[48:51]
	v_mfma_f32_16x16x32_bf16 v[32:35], v[168:171], v[226:229], 0
	v_mfma_f32_16x16x32_bf16 v[32:35], v[174:177], v[234:237], v[32:35]
	v_mfma_f32_16x16x32_bf16 v[16:19], v[168:171], v[230:233], 0
	v_mfma_f32_16x16x32_bf16 v[16:19], v[174:177], v[238:241], v[16:19]
	v_mfma_f32_16x16x32_bf16 v[12:15], v[178:181], v[230:233], 0
	v_mfma_f32_16x16x32_bf16 v[12:15], v[182:185], v[238:241], v[12:15]
	v_mfma_f32_16x16x32_bf16 v[28:31], v[178:181], v[226:229], 0
	v_mfma_f32_16x16x32_bf16 v[28:31], v[182:185], v[234:237], v[28:31]
	v_mfma_f32_16x16x32_bf16 v[44:47], v[178:181], v[214:217], 0
	v_mfma_f32_16x16x32_bf16 v[44:47], v[182:185], v[222:225], v[44:47]
	v_mfma_f32_16x16x32_bf16 v[60:63], v[178:181], v[210:213], 0
	v_mfma_f32_16x16x32_bf16 v[60:63], v[182:185], v[218:221], v[60:63]
	v_mfma_f32_16x16x32_bf16 v[56:59], v[194:197], v[210:213], 0
	v_mfma_f32_16x16x32_bf16 v[56:59], v[198:201], v[218:221], v[56:59]
	v_mfma_f32_16x16x32_bf16 v[40:43], v[194:197], v[214:217], 0
	v_mfma_f32_16x16x32_bf16 v[40:43], v[198:201], v[222:225], v[40:43]
	v_mfma_f32_16x16x32_bf16 v[24:27], v[194:197], v[226:229], 0
	v_mfma_f32_16x16x32_bf16 v[24:27], v[198:201], v[234:237], v[24:27]
	v_mfma_f32_16x16x32_bf16 v[8:11], v[194:197], v[230:233], 0
	v_mfma_f32_16x16x32_bf16 v[8:11], v[198:201], v[238:241], v[8:11]
	v_mfma_f32_16x16x32_bf16 v[4:7], v[202:205], v[230:233], 0
	v_mfma_f32_16x16x32_bf16 v[4:7], v[206:209], v[238:241], v[4:7]
	v_mfma_f32_16x16x32_bf16 v[20:23], v[202:205], v[226:229], 0
	v_mfma_f32_16x16x32_bf16 v[20:23], v[206:209], v[234:237], v[20:23]
	v_mfma_f32_16x16x32_bf16 v[36:39], v[202:205], v[214:217], 0
	v_mfma_f32_16x16x32_bf16 v[36:39], v[206:209], v[222:225], v[36:39]
	v_mfma_f32_16x16x32_bf16 v[52:55], v[202:205], v[210:213], 0
	v_mfma_f32_16x16x32_bf16 v[52:55], v[206:209], v[218:221], v[52:55]
	s_barrier
	ds_read_b128 v[168:171], v163
	ds_read_b128 v[174:177], v164
	ds_read_b128 v[178:181], v155
	ds_read_b128 v[182:185], v160
	ds_read_b128 v[194:197], v165
	ds_read_b128 v[198:201], v166
	ds_read_b128 v[202:205], v161
	ds_read_b128 v[206:209], v162
	s_mov_b32 m0, s34
	v_lshl_add_u64 v[242:243], s[70:71], 0, v[0:1]
	ds_read_b128 v[210:213], v153 offset:32768
	ds_read_b128 v[214:217], v153 offset:34816
	ds_read_b128 v[218:221], v154 offset:32768
	ds_read_b128 v[222:225], v154 offset:34816
	ds_read_b128 v[226:229], v153 offset:36864
	ds_read_b128 v[230:233], v153 offset:38912
	ds_read_b128 v[234:237], v154 offset:36864
	ds_read_b128 v[238:241], v154 offset:38912
	global_load_lds_dwordx4 v[242:243], off
	v_lshl_add_u64 v[244:245], v[242:243], 0, s[16:17]
	s_mov_b32 m0, s35
	s_nop 0
	global_load_lds_dwordx4 v[244:245], off
	v_lshl_add_u64 v[244:245], v[242:243], 0, s[0:1]
	s_mov_b32 m0, s38
	v_lshl_add_u64 v[242:243], v[242:243], 0, s[18:19]
	global_load_lds_dwordx4 v[244:245], off
	s_mov_b32 m0, s39
	s_nop 0
	global_load_lds_dwordx4 v[242:243], off
	s_waitcnt vmcnt(8)
	s_waitcnt lgkmcnt(0)
	s_barrier
	v_mfma_f32_16x16x32_bf16 v[128:131], v[168:171], v[210:213], v[128:131]
	v_mfma_f32_16x16x32_bf16 v[128:131], v[174:177], v[218:221], v[128:131]
	v_mfma_f32_16x16x32_bf16 v[112:115], v[174:177], v[222:225], v[112:115]
	v_mfma_f32_16x16x32_bf16 v[112:115], v[168:171], v[214:217], v[112:115]
	v_mfma_f32_16x16x32_bf16 v[96:99], v[168:171], v[226:229], v[96:99]
	v_mfma_f32_16x16x32_bf16 v[96:99], v[174:177], v[234:237], v[96:99]
	v_mfma_f32_16x16x32_bf16 v[80:83], v[174:177], v[238:241], v[80:83]
	v_mfma_f32_16x16x32_bf16 v[80:83], v[168:171], v[230:233], v[80:83]
	v_mfma_f32_16x16x32_bf16 v[76:79], v[178:181], v[230:233], v[76:79]
	v_mfma_f32_16x16x32_bf16 v[76:79], v[182:185], v[238:241], v[76:79]
	v_mfma_f32_16x16x32_bf16 v[92:95], v[182:185], v[234:237], v[92:95]
	v_mfma_f32_16x16x32_bf16 v[92:95], v[178:181], v[226:229], v[92:95]
	v_mfma_f32_16x16x32_bf16 v[108:111], v[178:181], v[214:217], v[108:111]
	v_mfma_f32_16x16x32_bf16 v[108:111], v[182:185], v[222:225], v[108:111]
	v_mfma_f32_16x16x32_bf16 v[124:127], v[182:185], v[218:221], v[124:127]
	v_mfma_f32_16x16x32_bf16 v[124:127], v[178:181], v[210:213], v[124:127]
	v_mfma_f32_16x16x32_bf16 v[120:123], v[194:197], v[210:213], v[120:123]
	v_mfma_f32_16x16x32_bf16 v[120:123], v[198:201], v[218:221], v[120:123]
	v_mfma_f32_16x16x32_bf16 v[104:107], v[198:201], v[222:225], v[104:107]
	v_mfma_f32_16x16x32_bf16 v[104:107], v[194:197], v[214:217], v[104:107]
	v_mfma_f32_16x16x32_bf16 v[88:91], v[194:197], v[226:229], v[88:91]
	v_mfma_f32_16x16x32_bf16 v[88:91], v[198:201], v[234:237], v[88:91]
	v_mfma_f32_16x16x32_bf16 v[72:75], v[198:201], v[238:241], v[72:75]
	v_mfma_f32_16x16x32_bf16 v[72:75], v[194:197], v[230:233], v[72:75]
	v_mfma_f32_16x16x32_bf16 v[68:71], v[202:205], v[230:233], v[68:71]
	v_mfma_f32_16x16x32_bf16 v[68:71], v[206:209], v[238:241], v[68:71]
	v_mfma_f32_16x16x32_bf16 v[84:87], v[206:209], v[234:237], v[84:87]
	v_mfma_f32_16x16x32_bf16 v[84:87], v[202:205], v[226:229], v[84:87]
	v_mfma_f32_16x16x32_bf16 v[100:103], v[202:205], v[214:217], v[100:103]
	v_mfma_f32_16x16x32_bf16 v[100:103], v[206:209], v[222:225], v[100:103]
	v_mfma_f32_16x16x32_bf16 v[116:119], v[206:209], v[218:221], v[116:119]
	v_mfma_f32_16x16x32_bf16 v[116:119], v[202:205], v[210:213], v[116:119]
	s_barrier
	s_add_i32 s70, s73, s3
	v_lshl_add_u64 v[242:243], v[140:141], 0, s[22:23]
	s_mov_b32 m0, s70
	ds_read_b128 v[210:213], v153 offset:49152
	ds_read_b128 v[214:217], v153 offset:51200
	ds_read_b128 v[218:221], v154 offset:49152
	ds_read_b128 v[222:225], v154 offset:51200
	ds_read_b128 v[226:229], v153 offset:53248
	ds_read_b128 v[230:233], v153 offset:55296
	ds_read_b128 v[234:237], v154 offset:53248
	ds_read_b128 v[238:241], v154 offset:55296
	global_load_lds_dwordx4 v[242:243], off
	v_lshl_add_u64 v[242:243], v[140:141], 0, s[24:25]
	s_add_i32 m0, s70, 0x2000
	s_add_i32 s70, s77, s3
	global_load_lds_dwordx4 v[242:243], off
	v_lshl_add_u64 v[242:243], v[140:141], 0, s[28:29]
	s_mov_b32 m0, s70
	v_lshl_add_u64 v[140:141], v[140:141], 0, s[36:37]
	global_load_lds_dwordx4 v[242:243], off
	s_add_i32 m0, s70, 0x2000
	s_nop 0
	global_load_lds_dwordx4 v[140:141], off
	s_waitcnt vmcnt(4)
	s_waitcnt lgkmcnt(0)
	s_barrier
	v_mfma_f32_16x16x32_bf16 v[64:67], v[168:171], v[210:213], v[64:67]
	v_mfma_f32_16x16x32_bf16 v[64:67], v[174:177], v[218:221], v[64:67]
	v_mfma_f32_16x16x32_bf16 v[48:51], v[174:177], v[222:225], v[48:51]
	v_mfma_f32_16x16x32_bf16 v[48:51], v[168:171], v[214:217], v[48:51]
	v_mfma_f32_16x16x32_bf16 v[32:35], v[168:171], v[226:229], v[32:35]
	v_mfma_f32_16x16x32_bf16 v[32:35], v[174:177], v[234:237], v[32:35]
	v_mfma_f32_16x16x32_bf16 v[16:19], v[174:177], v[238:241], v[16:19]
	v_mfma_f32_16x16x32_bf16 v[16:19], v[168:171], v[230:233], v[16:19]
	v_mfma_f32_16x16x32_bf16 v[12:15], v[178:181], v[230:233], v[12:15]
	v_mfma_f32_16x16x32_bf16 v[12:15], v[182:185], v[238:241], v[12:15]
	v_mfma_f32_16x16x32_bf16 v[28:31], v[182:185], v[234:237], v[28:31]
	v_mfma_f32_16x16x32_bf16 v[28:31], v[178:181], v[226:229], v[28:31]
	v_mfma_f32_16x16x32_bf16 v[44:47], v[178:181], v[214:217], v[44:47]
	v_mfma_f32_16x16x32_bf16 v[44:47], v[182:185], v[222:225], v[44:47]
	v_mfma_f32_16x16x32_bf16 v[60:63], v[182:185], v[218:221], v[60:63]
	v_mfma_f32_16x16x32_bf16 v[60:63], v[178:181], v[210:213], v[60:63]
	v_mfma_f32_16x16x32_bf16 v[56:59], v[194:197], v[210:213], v[56:59]
	v_mfma_f32_16x16x32_bf16 v[56:59], v[198:201], v[218:221], v[56:59]
	v_mfma_f32_16x16x32_bf16 v[40:43], v[198:201], v[222:225], v[40:43]
	v_mfma_f32_16x16x32_bf16 v[40:43], v[194:197], v[214:217], v[40:43]
	v_mfma_f32_16x16x32_bf16 v[24:27], v[194:197], v[226:229], v[24:27]
	v_mfma_f32_16x16x32_bf16 v[24:27], v[198:201], v[234:237], v[24:27]
	v_mfma_f32_16x16x32_bf16 v[8:11], v[198:201], v[238:241], v[8:11]
	v_mfma_f32_16x16x32_bf16 v[8:11], v[194:197], v[230:233], v[8:11]
	v_mfma_f32_16x16x32_bf16 v[4:7], v[202:205], v[230:233], v[4:7]
	v_mfma_f32_16x16x32_bf16 v[4:7], v[206:209], v[238:241], v[4:7]
	v_mfma_f32_16x16x32_bf16 v[20:23], v[206:209], v[234:237], v[20:23]
	v_mfma_f32_16x16x32_bf16 v[20:23], v[202:205], v[226:229], v[20:23]
	v_mfma_f32_16x16x32_bf16 v[36:39], v[202:205], v[214:217], v[36:39]
	v_mfma_f32_16x16x32_bf16 v[36:39], v[206:209], v[222:225], v[36:39]
	v_mfma_f32_16x16x32_bf16 v[52:55], v[206:209], v[218:221], v[52:55]
	v_mfma_f32_16x16x32_bf16 v[52:55], v[202:205], v[210:213], v[52:55]
	s_barrier
	s_add_i32 s83, s83, 2
	s_add_u32 s68, s68, 0x100
	s_addc_u32 s69, s69, 0
	s_cmp_gt_u32 s83, 13
.LBB0_1135:
	ds_read_b128 v[168:171], v145
	ds_read_b128 v[174:177], v146
	ds_read_b128 v[178:181], v147
	ds_read_b128 v[182:185], v148
	ds_read_b128 v[194:197], v149
	ds_read_b128 v[198:201], v150
	ds_read_b128 v[202:205], v151
	ds_read_b128 v[206:209], v152
	s_add_u32 s70, s26, s68
	s_addc_u32 s71, s27, s69
	s_add_u32 s70, s70, 0x100
	s_addc_u32 s71, s71, 0
	s_add_u32 s84, s81, s68
	s_addc_u32 s85, s82, s69
	s_cmpk_eq_i32 s68, 0x700
	s_cselect_b32 s85, s59, s85
	s_cselect_b32 s84, s80, s84
	s_cselect_b32 s71, s57, s71
	s_cselect_b32 s70, s79, s70
	v_lshl_add_u64 v[140:141], v[138:139], 0, s[68:69]
	v_lshl_add_u64 v[242:243], v[140:141], 0, s[22:23]
	s_add_i32 m0, s34, 0x8000
	s_mov_b64 s[86:87], 0x20080
	ds_read_b128 v[210:213], v153
	ds_read_b128 v[214:217], v153 offset:2048
	ds_read_b128 v[218:221], v154
	ds_read_b128 v[222:225], v154 offset:2048
	ds_read_b128 v[226:229], v153 offset:4096
	ds_read_b128 v[230:233], v153 offset:6144
	ds_read_b128 v[234:237], v154 offset:4096
	ds_read_b128 v[238:241], v154 offset:6144
	global_load_lds_dwordx4 v[242:243], off
	v_lshl_add_u64 v[242:243], v[140:141], 0, s[86:87]
	s_add_i32 m0, s34, 0xa000
	s_mov_b64 s[86:87], 0x60080
	global_load_lds_dwordx4 v[242:243], off
	v_lshl_add_u64 v[242:243], v[140:141], 0, s[24:25]
	s_add_i32 m0, s34, 0xc000
	v_lshl_add_u64 v[140:141], v[140:141], 0, s[86:87]
	global_load_lds_dwordx4 v[242:243], off
	s_add_i32 m0, s34, 0xe000
	s_nop 0
	global_load_lds_dwordx4 v[140:141], off
	s_waitcnt vmcnt(8)
	s_waitcnt lgkmcnt(0)
	s_barrier
	v_mfma_f32_16x16x32_bf16 v[128:131], v[168:171], v[210:213], v[128:131]
	v_mfma_f32_16x16x32_bf16 v[128:131], v[174:177], v[218:221], v[128:131]
	v_mfma_f32_16x16x32_bf16 v[112:115], v[174:177], v[222:225], v[112:115]
	v_mfma_f32_16x16x32_bf16 v[112:115], v[168:171], v[214:217], v[112:115]
	v_mfma_f32_16x16x32_bf16 v[96:99], v[168:171], v[226:229], v[96:99]
	v_mfma_f32_16x16x32_bf16 v[96:99], v[174:177], v[234:237], v[96:99]
	v_mfma_f32_16x16x32_bf16 v[80:83], v[174:177], v[238:241], v[80:83]
	v_mfma_f32_16x16x32_bf16 v[80:83], v[168:171], v[230:233], v[80:83]
	v_mfma_f32_16x16x32_bf16 v[76:79], v[178:181], v[230:233], v[76:79]
	v_mfma_f32_16x16x32_bf16 v[76:79], v[182:185], v[238:241], v[76:79]
	v_mfma_f32_16x16x32_bf16 v[92:95], v[182:185], v[234:237], v[92:95]
	v_mfma_f32_16x16x32_bf16 v[92:95], v[178:181], v[226:229], v[92:95]
	v_mfma_f32_16x16x32_bf16 v[108:111], v[178:181], v[214:217], v[108:111]
	v_mfma_f32_16x16x32_bf16 v[108:111], v[182:185], v[222:225], v[108:111]
	v_mfma_f32_16x16x32_bf16 v[124:127], v[182:185], v[218:221], v[124:127]
	v_mfma_f32_16x16x32_bf16 v[124:127], v[178:181], v[210:213], v[124:127]
	v_mfma_f32_16x16x32_bf16 v[120:123], v[194:197], v[210:213], v[120:123]
	v_mfma_f32_16x16x32_bf16 v[120:123], v[198:201], v[218:221], v[120:123]
	v_mfma_f32_16x16x32_bf16 v[104:107], v[198:201], v[222:225], v[104:107]
	v_mfma_f32_16x16x32_bf16 v[104:107], v[194:197], v[214:217], v[104:107]
	v_mfma_f32_16x16x32_bf16 v[88:91], v[194:197], v[226:229], v[88:91]
	v_mfma_f32_16x16x32_bf16 v[88:91], v[198:201], v[234:237], v[88:91]
	v_mfma_f32_16x16x32_bf16 v[72:75], v[198:201], v[238:241], v[72:75]
	v_mfma_f32_16x16x32_bf16 v[72:75], v[194:197], v[230:233], v[72:75]
	v_mfma_f32_16x16x32_bf16 v[68:71], v[202:205], v[230:233], v[68:71]
	v_mfma_f32_16x16x32_bf16 v[68:71], v[206:209], v[238:241], v[68:71]
	v_mfma_f32_16x16x32_bf16 v[84:87], v[206:209], v[234:237], v[84:87]
	v_mfma_f32_16x16x32_bf16 v[84:87], v[202:205], v[226:229], v[84:87]
	v_mfma_f32_16x16x32_bf16 v[100:103], v[202:205], v[214:217], v[100:103]
	v_mfma_f32_16x16x32_bf16 v[100:103], v[206:209], v[222:225], v[100:103]
	v_mfma_f32_16x16x32_bf16 v[116:119], v[206:209], v[218:221], v[116:119]
	v_mfma_f32_16x16x32_bf16 v[116:119], v[202:205], v[210:213], v[116:119]
	s_barrier
	v_lshl_add_u64 v[140:141], s[84:85], 0, v[158:159]
	s_add_i32 s84, s67, s3
	s_mov_b32 m0, s84
	ds_read_b128 v[210:213], v153 offset:16384
	ds_read_b128 v[214:217], v153 offset:18432
	ds_read_b128 v[218:221], v154 offset:16384
	ds_read_b128 v[222:225], v154 offset:18432
	ds_read_b128 v[226:229], v153 offset:20480
	ds_read_b128 v[230:233], v153 offset:22528
	ds_read_b128 v[234:237], v154 offset:20480
	ds_read_b128 v[238:241], v154 offset:22528
	global_load_lds_dwordx4 v[140:141], off
	v_lshl_add_u64 v[242:243], v[140:141], 0, s[0:1]
	s_add_i32 m0, s84, 0x2000
	s_add_i32 s84, s72, s3
	global_load_lds_dwordx4 v[242:243], off
	v_lshl_add_u64 v[242:243], v[140:141], 0, s[12:13]
	s_mov_b32 m0, s84
	s_nop 0
	global_load_lds_dwordx4 v[242:243], off
	v_lshl_add_u64 v[242:243], v[140:141], 0, s[14:15]
	s_add_i32 m0, s84, 0x2000
	s_nop 0
	global_load_lds_dwordx4 v[242:243], off
	s_waitcnt vmcnt(4)
	s_waitcnt lgkmcnt(0)
	s_barrier
	v_mfma_f32_16x16x32_bf16 v[64:67], v[168:171], v[210:213], v[64:67]
	v_mfma_f32_16x16x32_bf16 v[64:67], v[174:177], v[218:221], v[64:67]
	v_mfma_f32_16x16x32_bf16 v[48:51], v[174:177], v[222:225], v[48:51]
	v_mfma_f32_16x16x32_bf16 v[48:51], v[168:171], v[214:217], v[48:51]
	v_mfma_f32_16x16x32_bf16 v[32:35], v[168:171], v[226:229], v[32:35]
	v_mfma_f32_16x16x32_bf16 v[32:35], v[174:177], v[234:237], v[32:35]
	v_mfma_f32_16x16x32_bf16 v[16:19], v[174:177], v[238:241], v[16:19]
	v_mfma_f32_16x16x32_bf16 v[16:19], v[168:171], v[230:233], v[16:19]
	v_mfma_f32_16x16x32_bf16 v[12:15], v[178:181], v[230:233], v[12:15]
	v_mfma_f32_16x16x32_bf16 v[12:15], v[182:185], v[238:241], v[12:15]
	v_mfma_f32_16x16x32_bf16 v[28:31], v[182:185], v[234:237], v[28:31]
	v_mfma_f32_16x16x32_bf16 v[28:31], v[178:181], v[226:229], v[28:31]
	v_mfma_f32_16x16x32_bf16 v[44:47], v[178:181], v[214:217], v[44:47]
	v_mfma_f32_16x16x32_bf16 v[44:47], v[182:185], v[222:225], v[44:47]
	v_mfma_f32_16x16x32_bf16 v[60:63], v[182:185], v[218:221], v[60:63]
	v_mfma_f32_16x16x32_bf16 v[60:63], v[178:181], v[210:213], v[60:63]
	v_mfma_f32_16x16x32_bf16 v[56:59], v[194:197], v[210:213], v[56:59]
	v_mfma_f32_16x16x32_bf16 v[56:59], v[198:201], v[218:221], v[56:59]
	v_mfma_f32_16x16x32_bf16 v[40:43], v[198:201], v[222:225], v[40:43]
	v_mfma_f32_16x16x32_bf16 v[40:43], v[194:197], v[214:217], v[40:43]
	v_mfma_f32_16x16x32_bf16 v[24:27], v[194:197], v[226:229], v[24:27]
	v_mfma_f32_16x16x32_bf16 v[24:27], v[198:201], v[234:237], v[24:27]
	v_mfma_f32_16x16x32_bf16 v[8:11], v[198:201], v[238:241], v[8:11]
	v_mfma_f32_16x16x32_bf16 v[8:11], v[194:197], v[230:233], v[8:11]
	v_mfma_f32_16x16x32_bf16 v[4:7], v[202:205], v[230:233], v[4:7]
	v_mfma_f32_16x16x32_bf16 v[4:7], v[206:209], v[238:241], v[4:7]
	v_mfma_f32_16x16x32_bf16 v[20:23], v[206:209], v[234:237], v[20:23]
	v_mfma_f32_16x16x32_bf16 v[20:23], v[202:205], v[226:229], v[20:23]
	v_mfma_f32_16x16x32_bf16 v[36:39], v[202:205], v[214:217], v[36:39]
	v_mfma_f32_16x16x32_bf16 v[36:39], v[206:209], v[222:225], v[36:39]
	v_mfma_f32_16x16x32_bf16 v[52:55], v[206:209], v[218:221], v[52:55]
	v_mfma_f32_16x16x32_bf16 v[52:55], v[202:205], v[210:213], v[52:55]
	s_barrier
	ds_read_b128 v[168:171], v163
	ds_read_b128 v[174:177], v164
	ds_read_b128 v[178:181], v155
	ds_read_b128 v[182:185], v160
	ds_read_b128 v[194:197], v165
	ds_read_b128 v[198:201], v166
	ds_read_b128 v[202:205], v161
	ds_read_b128 v[206:209], v162
	s_mov_b32 m0, s34
	v_lshl_add_u64 v[242:243], s[70:71], 0, v[0:1]
	ds_read_b128 v[210:213], v153 offset:32768
	ds_read_b128 v[214:217], v153 offset:34816
	ds_read_b128 v[218:221], v154 offset:32768
	ds_read_b128 v[222:225], v154 offset:34816
	ds_read_b128 v[226:229], v153 offset:36864
	ds_read_b128 v[230:233], v153 offset:38912
	ds_read_b128 v[234:237], v154 offset:36864
	ds_read_b128 v[238:241], v154 offset:38912
	global_load_lds_dwordx4 v[242:243], off
	v_lshl_add_u64 v[244:245], v[242:243], 0, s[16:17]
	s_mov_b32 m0, s35
	s_nop 0
	global_load_lds_dwordx4 v[244:245], off
	v_lshl_add_u64 v[244:245], v[242:243], 0, s[0:1]
	s_mov_b32 m0, s38
	v_lshl_add_u64 v[242:243], v[242:243], 0, s[18:19]
	global_load_lds_dwordx4 v[244:245], off
	s_mov_b32 m0, s39
	s_nop 0
	global_load_lds_dwordx4 v[242:243], off
	s_waitcnt vmcnt(8)
	s_waitcnt lgkmcnt(0)
	s_barrier
	v_mfma_f32_16x16x32_bf16 v[128:131], v[168:171], v[210:213], v[128:131]
	v_mfma_f32_16x16x32_bf16 v[128:131], v[174:177], v[218:221], v[128:131]
	v_mfma_f32_16x16x32_bf16 v[112:115], v[174:177], v[222:225], v[112:115]
	v_mfma_f32_16x16x32_bf16 v[112:115], v[168:171], v[214:217], v[112:115]
	v_mfma_f32_16x16x32_bf16 v[96:99], v[168:171], v[226:229], v[96:99]
	v_mfma_f32_16x16x32_bf16 v[96:99], v[174:177], v[234:237], v[96:99]
	v_mfma_f32_16x16x32_bf16 v[80:83], v[174:177], v[238:241], v[80:83]
	v_mfma_f32_16x16x32_bf16 v[80:83], v[168:171], v[230:233], v[80:83]
	v_mfma_f32_16x16x32_bf16 v[76:79], v[178:181], v[230:233], v[76:79]
	v_mfma_f32_16x16x32_bf16 v[76:79], v[182:185], v[238:241], v[76:79]
	v_mfma_f32_16x16x32_bf16 v[92:95], v[182:185], v[234:237], v[92:95]
	v_mfma_f32_16x16x32_bf16 v[92:95], v[178:181], v[226:229], v[92:95]
	v_mfma_f32_16x16x32_bf16 v[108:111], v[178:181], v[214:217], v[108:111]
	v_mfma_f32_16x16x32_bf16 v[108:111], v[182:185], v[222:225], v[108:111]
	v_mfma_f32_16x16x32_bf16 v[124:127], v[182:185], v[218:221], v[124:127]
	v_mfma_f32_16x16x32_bf16 v[124:127], v[178:181], v[210:213], v[124:127]
	v_mfma_f32_16x16x32_bf16 v[120:123], v[194:197], v[210:213], v[120:123]
	v_mfma_f32_16x16x32_bf16 v[120:123], v[198:201], v[218:221], v[120:123]
	v_mfma_f32_16x16x32_bf16 v[104:107], v[198:201], v[222:225], v[104:107]
	v_mfma_f32_16x16x32_bf16 v[104:107], v[194:197], v[214:217], v[104:107]
	v_mfma_f32_16x16x32_bf16 v[88:91], v[194:197], v[226:229], v[88:91]
	v_mfma_f32_16x16x32_bf16 v[88:91], v[198:201], v[234:237], v[88:91]
	v_mfma_f32_16x16x32_bf16 v[72:75], v[198:201], v[238:241], v[72:75]
	v_mfma_f32_16x16x32_bf16 v[72:75], v[194:197], v[230:233], v[72:75]
	v_mfma_f32_16x16x32_bf16 v[68:71], v[202:205], v[230:233], v[68:71]
	v_mfma_f32_16x16x32_bf16 v[68:71], v[206:209], v[238:241], v[68:71]
	v_mfma_f32_16x16x32_bf16 v[84:87], v[206:209], v[234:237], v[84:87]
	v_mfma_f32_16x16x32_bf16 v[84:87], v[202:205], v[226:229], v[84:87]
	v_mfma_f32_16x16x32_bf16 v[100:103], v[202:205], v[214:217], v[100:103]
	v_mfma_f32_16x16x32_bf16 v[100:103], v[206:209], v[222:225], v[100:103]
	v_mfma_f32_16x16x32_bf16 v[116:119], v[206:209], v[218:221], v[116:119]
	v_mfma_f32_16x16x32_bf16 v[116:119], v[202:205], v[210:213], v[116:119]
	s_barrier
	s_add_i32 s70, s73, s3
	v_lshl_add_u64 v[242:243], v[140:141], 0, s[22:23]
	s_mov_b32 m0, s70
	ds_read_b128 v[210:213], v153 offset:49152
	ds_read_b128 v[214:217], v153 offset:51200
	ds_read_b128 v[218:221], v154 offset:49152
	ds_read_b128 v[222:225], v154 offset:51200
	ds_read_b128 v[226:229], v153 offset:53248
	ds_read_b128 v[230:233], v153 offset:55296
	ds_read_b128 v[234:237], v154 offset:53248
	ds_read_b128 v[238:241], v154 offset:55296
	global_load_lds_dwordx4 v[242:243], off
	v_lshl_add_u64 v[242:243], v[140:141], 0, s[24:25]
	s_add_i32 m0, s70, 0x2000
	s_add_i32 s70, s77, s3
	global_load_lds_dwordx4 v[242:243], off
	v_lshl_add_u64 v[242:243], v[140:141], 0, s[28:29]
	s_mov_b32 m0, s70
	v_lshl_add_u64 v[140:141], v[140:141], 0, s[36:37]
	global_load_lds_dwordx4 v[242:243], off
	s_add_i32 m0, s70, 0x2000
	s_nop 0
	global_load_lds_dwordx4 v[140:141], off
	s_waitcnt vmcnt(4)
	s_waitcnt lgkmcnt(0)
	s_barrier
	v_mfma_f32_16x16x32_bf16 v[64:67], v[168:171], v[210:213], v[64:67]
	v_mfma_f32_16x16x32_bf16 v[64:67], v[174:177], v[218:221], v[64:67]
	v_mfma_f32_16x16x32_bf16 v[48:51], v[174:177], v[222:225], v[48:51]
	v_mfma_f32_16x16x32_bf16 v[48:51], v[168:171], v[214:217], v[48:51]
	v_mfma_f32_16x16x32_bf16 v[32:35], v[168:171], v[226:229], v[32:35]
	v_mfma_f32_16x16x32_bf16 v[32:35], v[174:177], v[234:237], v[32:35]
	v_mfma_f32_16x16x32_bf16 v[16:19], v[174:177], v[238:241], v[16:19]
	v_mfma_f32_16x16x32_bf16 v[16:19], v[168:171], v[230:233], v[16:19]
	v_mfma_f32_16x16x32_bf16 v[12:15], v[178:181], v[230:233], v[12:15]
	v_mfma_f32_16x16x32_bf16 v[12:15], v[182:185], v[238:241], v[12:15]
	v_mfma_f32_16x16x32_bf16 v[28:31], v[182:185], v[234:237], v[28:31]
	v_mfma_f32_16x16x32_bf16 v[28:31], v[178:181], v[226:229], v[28:31]
	v_mfma_f32_16x16x32_bf16 v[44:47], v[178:181], v[214:217], v[44:47]
	v_mfma_f32_16x16x32_bf16 v[44:47], v[182:185], v[222:225], v[44:47]
	v_mfma_f32_16x16x32_bf16 v[60:63], v[182:185], v[218:221], v[60:63]
	v_mfma_f32_16x16x32_bf16 v[60:63], v[178:181], v[210:213], v[60:63]
	v_mfma_f32_16x16x32_bf16 v[56:59], v[194:197], v[210:213], v[56:59]
	v_mfma_f32_16x16x32_bf16 v[56:59], v[198:201], v[218:221], v[56:59]
	v_mfma_f32_16x16x32_bf16 v[40:43], v[198:201], v[222:225], v[40:43]
	v_mfma_f32_16x16x32_bf16 v[40:43], v[194:197], v[214:217], v[40:43]
	v_mfma_f32_16x16x32_bf16 v[24:27], v[194:197], v[226:229], v[24:27]
	v_mfma_f32_16x16x32_bf16 v[24:27], v[198:201], v[234:237], v[24:27]
	v_mfma_f32_16x16x32_bf16 v[8:11], v[198:201], v[238:241], v[8:11]
	v_mfma_f32_16x16x32_bf16 v[8:11], v[194:197], v[230:233], v[8:11]
	v_mfma_f32_16x16x32_bf16 v[4:7], v[202:205], v[230:233], v[4:7]
	v_mfma_f32_16x16x32_bf16 v[4:7], v[206:209], v[238:241], v[4:7]
	v_mfma_f32_16x16x32_bf16 v[20:23], v[206:209], v[234:237], v[20:23]
	v_mfma_f32_16x16x32_bf16 v[20:23], v[202:205], v[226:229], v[20:23]
	v_mfma_f32_16x16x32_bf16 v[36:39], v[202:205], v[214:217], v[36:39]
	v_mfma_f32_16x16x32_bf16 v[36:39], v[206:209], v[222:225], v[36:39]
	v_mfma_f32_16x16x32_bf16 v[52:55], v[206:209], v[218:221], v[52:55]
	v_mfma_f32_16x16x32_bf16 v[52:55], v[202:205], v[210:213], v[52:55]
	s_barrier
	s_add_i32 s83, s83, 2
	s_add_u32 s68, s68, 0x100
	s_addc_u32 s69, s69, 0
	s_cmp_gt_u32 s83, 13
	s_cbranch_scc0 .LBB0_1135
	s_and_b64 vcc, exec, s[40:41]
	s_cbranch_vccz .LBB0_1138
	s_barrier

.LBB0_1371:
	v_add_u32_e32 v147, s64, v143
	v_add_u32_e32 v152, s64, v144
	ds_read_b128 v[148:151], v147
	ds_read_b128 v[152:155], v152
	v_add_u32_e32 v147, s65, v143
	v_add_u32_e32 v162, s65, v144
	s_add_u32 s58, s18, s56
	ds_read_b128 v[158:161], v147
	ds_read_b128 v[162:165], v162
	v_add_u32_e32 v147, s66, v143
	s_addc_u32 s59, s19, s57
	v_add_u32_e32 v166, s66, v144
	ds_read_b128 v[170:173], v147
	ds_read_b128 v[174:177], v166
	v_add_u32_e32 v147, s67, v143
	s_add_u32 s58, s58, 0x100
	v_add_u32_e32 v166, s67, v144
	ds_read_b128 v[178:181], v147
	ds_read_b128 v[182:185], v166
	s_addc_u32 s59, s59, 0
	s_add_u32 s78, s53, s56
	s_addc_u32 s79, s72, s57
	s_cmpk_eq_i32 s56, 0x1f00
	s_cselect_b32 s79, s49, s79
	s_cselect_b32 s78, s76, s78
	s_cselect_b32 s59, s51, s59
	s_cselect_b32 s58, s73, s58
	v_lshl_add_u64 v[166:167], v[140:141], 0, s[56:57]
	v_lshl_add_u64 v[218:219], v[166:167], 0, s[24:25]
	s_add_i32 m0, s35, 0x8000
	ds_read_b128 v[186:189], v145
	ds_read_b128 v[190:193], v145 offset:2048
	ds_read_b128 v[194:197], v146
	ds_read_b128 v[198:201], v146 offset:2048
	ds_read_b128 v[202:205], v145 offset:4096
	ds_read_b128 v[206:209], v145 offset:6144
	ds_read_b128 v[210:213], v146 offset:4096
	ds_read_b128 v[214:217], v146 offset:6144
	global_load_lds_dwordx4 v[218:219], off
	v_lshl_add_u64 v[218:219], v[166:167], 0, s[44:45]
	s_add_i32 m0, s35, 0xa000
	s_nop 0
	global_load_lds_dwordx4 v[218:219], off
	v_lshl_add_u64 v[218:219], v[166:167], 0, s[28:29]
	s_add_i32 m0, s35, 0xc000
	v_lshl_add_u64 v[166:167], v[166:167], 0, s[46:47]
	global_load_lds_dwordx4 v[218:219], off
	s_add_i32 m0, s35, 0xe000
	s_nop 0
	global_load_lds_dwordx4 v[166:167], off
	s_waitcnt vmcnt(8)
	s_waitcnt lgkmcnt(0)
	s_barrier
	v_mfma_f32_16x16x32_bf16 v[128:131], v[148:151], v[186:189], v[128:131]
	v_mfma_f32_16x16x32_bf16 v[128:131], v[152:155], v[194:197], v[128:131]
	v_mfma_f32_16x16x32_bf16 v[112:115], v[152:155], v[198:201], v[112:115]
	v_mfma_f32_16x16x32_bf16 v[112:115], v[148:151], v[190:193], v[112:115]
	v_mfma_f32_16x16x32_bf16 v[96:99], v[148:151], v[202:205], v[96:99]
	v_mfma_f32_16x16x32_bf16 v[96:99], v[152:155], v[210:213], v[96:99]
	v_mfma_f32_16x16x32_bf16 v[80:83], v[152:155], v[214:217], v[80:83]
	v_mfma_f32_16x16x32_bf16 v[80:83], v[148:151], v[206:209], v[80:83]
	v_mfma_f32_16x16x32_bf16 v[76:79], v[158:161], v[206:209], v[76:79]
	v_mfma_f32_16x16x32_bf16 v[76:79], v[162:165], v[214:217], v[76:79]
	v_mfma_f32_16x16x32_bf16 v[92:95], v[162:165], v[210:213], v[92:95]
	v_mfma_f32_16x16x32_bf16 v[92:95], v[158:161], v[202:205], v[92:95]
	v_mfma_f32_16x16x32_bf16 v[108:111], v[158:161], v[190:193], v[108:111]
	v_mfma_f32_16x16x32_bf16 v[108:111], v[162:165], v[198:201], v[108:111]
	v_mfma_f32_16x16x32_bf16 v[124:127], v[162:165], v[194:197], v[124:127]
	v_mfma_f32_16x16x32_bf16 v[124:127], v[158:161], v[186:189], v[124:127]
	v_mfma_f32_16x16x32_bf16 v[120:123], v[170:173], v[186:189], v[120:123]
	v_mfma_f32_16x16x32_bf16 v[120:123], v[174:177], v[194:197], v[120:123]
	v_mfma_f32_16x16x32_bf16 v[104:107], v[174:177], v[198:201], v[104:107]
	v_mfma_f32_16x16x32_bf16 v[104:107], v[170:173], v[190:193], v[104:107]
	v_mfma_f32_16x16x32_bf16 v[88:91], v[170:173], v[202:205], v[88:91]
	v_mfma_f32_16x16x32_bf16 v[88:91], v[174:177], v[210:213], v[88:91]
	v_mfma_f32_16x16x32_bf16 v[72:75], v[174:177], v[214:217], v[72:75]
	v_mfma_f32_16x16x32_bf16 v[72:75], v[170:173], v[206:209], v[72:75]
	v_mfma_f32_16x16x32_bf16 v[68:71], v[178:181], v[206:209], v[68:71]
	v_mfma_f32_16x16x32_bf16 v[68:71], v[182:185], v[214:217], v[68:71]
	v_mfma_f32_16x16x32_bf16 v[84:87], v[182:185], v[210:213], v[84:87]
	v_mfma_f32_16x16x32_bf16 v[84:87], v[178:181], v[202:205], v[84:87]
	v_mfma_f32_16x16x32_bf16 v[100:103], v[178:181], v[190:193], v[100:103]
	v_mfma_f32_16x16x32_bf16 v[100:103], v[182:185], v[198:201], v[100:103]
	v_mfma_f32_16x16x32_bf16 v[116:119], v[182:185], v[194:197], v[116:119]
	v_mfma_f32_16x16x32_bf16 v[116:119], v[178:181], v[186:189], v[116:119]
	s_barrier
	v_lshl_add_u64 v[166:167], s[78:79], 0, v[132:133]
	s_add_i32 s78, s64, s34
	s_mov_b32 m0, s78
	ds_read_b128 v[186:189], v145 offset:16384
	ds_read_b128 v[190:193], v145 offset:18432
	ds_read_b128 v[194:197], v146 offset:16384
	ds_read_b128 v[198:201], v146 offset:18432
	ds_read_b128 v[202:205], v145 offset:20480
	ds_read_b128 v[206:209], v145 offset:22528
	ds_read_b128 v[210:213], v146 offset:20480
	ds_read_b128 v[214:217], v146 offset:22528
	global_load_lds_dwordx4 v[166:167], off
	v_lshl_add_u64 v[218:219], v[166:167], 0, s[10:11]
	s_add_i32 m0, s78, 0x2000
	s_add_i32 s78, s66, s34
	global_load_lds_dwordx4 v[218:219], off
	v_lshl_add_u64 v[218:219], v[166:167], 0, s[14:15]
	s_mov_b32 m0, s78
	s_nop 0
	global_load_lds_dwordx4 v[218:219], off
	v_lshl_add_u64 v[218:219], v[166:167], 0, s[16:17]
	s_add_i32 m0, s78, 0x2000
	s_nop 0
	global_load_lds_dwordx4 v[218:219], off
	s_waitcnt vmcnt(4)
	s_waitcnt lgkmcnt(0)
	s_barrier
	v_mfma_f32_16x16x32_bf16 v[64:67], v[148:151], v[186:189], v[64:67]
	v_mfma_f32_16x16x32_bf16 v[64:67], v[152:155], v[194:197], v[64:67]
	v_mfma_f32_16x16x32_bf16 v[48:51], v[152:155], v[198:201], v[48:51]
	v_mfma_f32_16x16x32_bf16 v[48:51], v[148:151], v[190:193], v[48:51]
	v_mfma_f32_16x16x32_bf16 v[32:35], v[148:151], v[202:205], v[32:35]
	v_mfma_f32_16x16x32_bf16 v[32:35], v[152:155], v[210:213], v[32:35]
	v_mfma_f32_16x16x32_bf16 v[16:19], v[152:155], v[214:217], v[16:19]
	v_mfma_f32_16x16x32_bf16 v[16:19], v[148:151], v[206:209], v[16:19]
	v_mfma_f32_16x16x32_bf16 v[12:15], v[158:161], v[206:209], v[12:15]
	v_mfma_f32_16x16x32_bf16 v[12:15], v[162:165], v[214:217], v[12:15]
	v_mfma_f32_16x16x32_bf16 v[28:31], v[162:165], v[210:213], v[28:31]
	v_mfma_f32_16x16x32_bf16 v[28:31], v[158:161], v[202:205], v[28:31]
	v_mfma_f32_16x16x32_bf16 v[44:47], v[158:161], v[190:193], v[44:47]
	v_mfma_f32_16x16x32_bf16 v[44:47], v[162:165], v[198:201], v[44:47]
	v_mfma_f32_16x16x32_bf16 v[60:63], v[162:165], v[194:197], v[60:63]
	v_mfma_f32_16x16x32_bf16 v[60:63], v[158:161], v[186:189], v[60:63]
	v_mfma_f32_16x16x32_bf16 v[56:59], v[170:173], v[186:189], v[56:59]
	v_mfma_f32_16x16x32_bf16 v[56:59], v[174:177], v[194:197], v[56:59]
	v_mfma_f32_16x16x32_bf16 v[40:43], v[174:177], v[198:201], v[40:43]
	v_mfma_f32_16x16x32_bf16 v[40:43], v[170:173], v[190:193], v[40:43]
	v_mfma_f32_16x16x32_bf16 v[24:27], v[170:173], v[202:205], v[24:27]
	v_mfma_f32_16x16x32_bf16 v[24:27], v[174:177], v[210:213], v[24:27]
	v_mfma_f32_16x16x32_bf16 v[8:11], v[174:177], v[214:217], v[8:11]
	v_mfma_f32_16x16x32_bf16 v[8:11], v[170:173], v[206:209], v[8:11]
	v_mfma_f32_16x16x32_bf16 v[4:7], v[178:181], v[206:209], v[4:7]
	v_mfma_f32_16x16x32_bf16 v[4:7], v[182:185], v[214:217], v[4:7]
	v_mfma_f32_16x16x32_bf16 v[20:23], v[182:185], v[210:213], v[20:23]
	v_mfma_f32_16x16x32_bf16 v[20:23], v[178:181], v[202:205], v[20:23]
	v_mfma_f32_16x16x32_bf16 v[36:39], v[178:181], v[190:193], v[36:39]
	v_mfma_f32_16x16x32_bf16 v[36:39], v[182:185], v[198:201], v[36:39]
	v_mfma_f32_16x16x32_bf16 v[52:55], v[182:185], v[194:197], v[52:55]
	v_mfma_f32_16x16x32_bf16 v[52:55], v[178:181], v[186:189], v[52:55]
	s_barrier
	v_add_u32_e32 v147, s70, v143
	v_add_u32_e32 v152, s70, v144
	ds_read_b128 v[148:151], v147
	ds_read_b128 v[152:155], v152
	v_add_u32_e32 v147, s68, v143
	v_add_u32_e32 v162, s68, v144
	ds_read_b128 v[158:161], v147
	ds_read_b128 v[162:165], v162
	v_add_u32_e32 v147, s71, v143
	v_add_u32_e32 v169, s71, v144
	ds_read_b128 v[170:173], v147
	ds_read_b128 v[174:177], v169
	v_add_u32_e32 v147, s69, v143
	v_add_u32_e32 v169, s69, v144
	ds_read_b128 v[178:181], v147
	ds_read_b128 v[182:185], v169
	s_mov_b32 m0, s35
	v_lshl_add_u64 v[218:219], s[58:59], 0, v[0:1]
	ds_read_b128 v[186:189], v145 offset:32768
	ds_read_b128 v[190:193], v145 offset:34816
	ds_read_b128 v[194:197], v146 offset:32768
	ds_read_b128 v[198:201], v146 offset:34816
	ds_read_b128 v[202:205], v145 offset:36864
	ds_read_b128 v[206:209], v145 offset:38912
	ds_read_b128 v[210:213], v146 offset:36864
	ds_read_b128 v[214:217], v146 offset:38912
	global_load_lds_dwordx4 v[218:219], off
	v_lshl_add_u64 v[220:221], v[218:219], 0, s[20:21]
	s_mov_b32 m0, s39
	s_nop 0
	global_load_lds_dwordx4 v[220:221], off
	v_lshl_add_u64 v[220:221], v[218:219], 0, s[10:11]
	s_mov_b32 m0, s60
	v_lshl_add_u64 v[218:219], v[218:219], 0, s[22:23]
	global_load_lds_dwordx4 v[220:221], off
	s_mov_b32 m0, s61
	s_nop 0
	global_load_lds_dwordx4 v[218:219], off
	s_waitcnt vmcnt(8)
	s_waitcnt lgkmcnt(0)
	s_barrier
	v_mfma_f32_16x16x32_bf16 v[128:131], v[148:151], v[186:189], v[128:131]
	v_mfma_f32_16x16x32_bf16 v[128:131], v[152:155], v[194:197], v[128:131]
	v_mfma_f32_16x16x32_bf16 v[112:115], v[152:155], v[198:201], v[112:115]
	v_mfma_f32_16x16x32_bf16 v[112:115], v[148:151], v[190:193], v[112:115]
	v_mfma_f32_16x16x32_bf16 v[96:99], v[148:151], v[202:205], v[96:99]
	v_mfma_f32_16x16x32_bf16 v[96:99], v[152:155], v[210:213], v[96:99]
	v_mfma_f32_16x16x32_bf16 v[80:83], v[152:155], v[214:217], v[80:83]
	v_mfma_f32_16x16x32_bf16 v[80:83], v[148:151], v[206:209], v[80:83]
	v_mfma_f32_16x16x32_bf16 v[76:79], v[158:161], v[206:209], v[76:79]
	v_mfma_f32_16x16x32_bf16 v[76:79], v[162:165], v[214:217], v[76:79]
	v_mfma_f32_16x16x32_bf16 v[92:95], v[162:165], v[210:213], v[92:95]
	v_mfma_f32_16x16x32_bf16 v[92:95], v[158:161], v[202:205], v[92:95]
	v_mfma_f32_16x16x32_bf16 v[108:111], v[158:161], v[190:193], v[108:111]
	v_mfma_f32_16x16x32_bf16 v[108:111], v[162:165], v[198:201], v[108:111]
	v_mfma_f32_16x16x32_bf16 v[124:127], v[162:165], v[194:197], v[124:127]
	v_mfma_f32_16x16x32_bf16 v[124:127], v[158:161], v[186:189], v[124:127]
	v_mfma_f32_16x16x32_bf16 v[120:123], v[170:173], v[186:189], v[120:123]
	v_mfma_f32_16x16x32_bf16 v[120:123], v[174:177], v[194:197], v[120:123]
	v_mfma_f32_16x16x32_bf16 v[104:107], v[174:177], v[198:201], v[104:107]
	v_mfma_f32_16x16x32_bf16 v[104:107], v[170:173], v[190:193], v[104:107]
	v_mfma_f32_16x16x32_bf16 v[88:91], v[170:173], v[202:205], v[88:91]
	v_mfma_f32_16x16x32_bf16 v[88:91], v[174:177], v[210:213], v[88:91]
	v_mfma_f32_16x16x32_bf16 v[72:75], v[174:177], v[214:217], v[72:75]
	v_mfma_f32_16x16x32_bf16 v[72:75], v[170:173], v[206:209], v[72:75]
	v_mfma_f32_16x16x32_bf16 v[68:71], v[178:181], v[206:209], v[68:71]
	v_mfma_f32_16x16x32_bf16 v[68:71], v[182:185], v[214:217], v[68:71]
	v_mfma_f32_16x16x32_bf16 v[84:87], v[182:185], v[210:213], v[84:87]
	v_mfma_f32_16x16x32_bf16 v[84:87], v[178:181], v[202:205], v[84:87]
	v_mfma_f32_16x16x32_bf16 v[100:103], v[178:181], v[190:193], v[100:103]
	v_mfma_f32_16x16x32_bf16 v[100:103], v[182:185], v[198:201], v[100:103]
	v_mfma_f32_16x16x32_bf16 v[116:119], v[182:185], v[194:197], v[116:119]
	v_mfma_f32_16x16x32_bf16 v[116:119], v[178:181], v[186:189], v[116:119]
	s_barrier
	s_add_i32 s58, s70, s34
	v_lshl_add_u64 v[218:219], v[166:167], 0, s[24:25]
	s_mov_b32 m0, s58
	ds_read_b128 v[186:189], v145 offset:49152
	ds_read_b128 v[190:193], v145 offset:51200
	ds_read_b128 v[194:197], v146 offset:49152
	ds_read_b128 v[198:201], v146 offset:51200
	ds_read_b128 v[202:205], v145 offset:53248
	ds_read_b128 v[206:209], v145 offset:55296
	ds_read_b128 v[210:213], v146 offset:53248
	ds_read_b128 v[214:217], v146 offset:55296
	global_load_lds_dwordx4 v[218:219], off
	v_lshl_add_u64 v[218:219], v[166:167], 0, s[28:29]
	s_add_i32 m0, s58, 0x2000
	s_add_i32 s58, s71, s34
	global_load_lds_dwordx4 v[218:219], off
	v_lshl_add_u64 v[218:219], v[166:167], 0, s[36:37]
	s_mov_b32 m0, s58
	v_lshl_add_u64 v[166:167], v[166:167], 0, s[40:41]
	global_load_lds_dwordx4 v[218:219], off
	s_add_i32 m0, s58, 0x2000
	s_nop 0
	global_load_lds_dwordx4 v[166:167], off
	s_waitcnt vmcnt(4)
	s_waitcnt lgkmcnt(0)
	s_barrier
	v_mfma_f32_16x16x32_bf16 v[64:67], v[148:151], v[186:189], v[64:67]
	v_mfma_f32_16x16x32_bf16 v[64:67], v[152:155], v[194:197], v[64:67]
	v_mfma_f32_16x16x32_bf16 v[48:51], v[152:155], v[198:201], v[48:51]
	v_mfma_f32_16x16x32_bf16 v[48:51], v[148:151], v[190:193], v[48:51]
	v_mfma_f32_16x16x32_bf16 v[32:35], v[148:151], v[202:205], v[32:35]
	v_mfma_f32_16x16x32_bf16 v[32:35], v[152:155], v[210:213], v[32:35]
	v_mfma_f32_16x16x32_bf16 v[16:19], v[152:155], v[214:217], v[16:19]
	v_mfma_f32_16x16x32_bf16 v[16:19], v[148:151], v[206:209], v[16:19]
	v_mfma_f32_16x16x32_bf16 v[12:15], v[158:161], v[206:209], v[12:15]
	v_mfma_f32_16x16x32_bf16 v[12:15], v[162:165], v[214:217], v[12:15]
	v_mfma_f32_16x16x32_bf16 v[28:31], v[162:165], v[210:213], v[28:31]
	v_mfma_f32_16x16x32_bf16 v[28:31], v[158:161], v[202:205], v[28:31]
	v_mfma_f32_16x16x32_bf16 v[44:47], v[158:161], v[190:193], v[44:47]
	v_mfma_f32_16x16x32_bf16 v[44:47], v[162:165], v[198:201], v[44:47]
	v_mfma_f32_16x16x32_bf16 v[60:63], v[162:165], v[194:197], v[60:63]
	v_mfma_f32_16x16x32_bf16 v[60:63], v[158:161], v[186:189], v[60:63]
	v_mfma_f32_16x16x32_bf16 v[56:59], v[170:173], v[186:189], v[56:59]
	v_mfma_f32_16x16x32_bf16 v[56:59], v[174:177], v[194:197], v[56:59]
	v_mfma_f32_16x16x32_bf16 v[40:43], v[174:177], v[198:201], v[40:43]
	v_mfma_f32_16x16x32_bf16 v[40:43], v[170:173], v[190:193], v[40:43]
	v_mfma_f32_16x16x32_bf16 v[24:27], v[170:173], v[202:205], v[24:27]
	v_mfma_f32_16x16x32_bf16 v[24:27], v[174:177], v[210:213], v[24:27]
	v_mfma_f32_16x16x32_bf16 v[8:11], v[174:177], v[214:217], v[8:11]
	v_mfma_f32_16x16x32_bf16 v[8:11], v[170:173], v[206:209], v[8:11]
	v_mfma_f32_16x16x32_bf16 v[4:7], v[178:181], v[206:209], v[4:7]
	v_mfma_f32_16x16x32_bf16 v[4:7], v[182:185], v[214:217], v[4:7]
	v_mfma_f32_16x16x32_bf16 v[20:23], v[182:185], v[210:213], v[20:23]
	v_mfma_f32_16x16x32_bf16 v[20:23], v[178:181], v[202:205], v[20:23]
	v_mfma_f32_16x16x32_bf16 v[36:39], v[178:181], v[190:193], v[36:39]
	v_mfma_f32_16x16x32_bf16 v[36:39], v[182:185], v[198:201], v[36:39]
	v_mfma_f32_16x16x32_bf16 v[52:55], v[182:185], v[194:197], v[52:55]
	v_mfma_f32_16x16x32_bf16 v[52:55], v[178:181], v[186:189], v[52:55]
	s_barrier
	s_add_i32 s77, s77, 2
	s_add_u32 s56, s56, 0x100
	s_addc_u32 s57, s57, 0
	s_cmp_gt_u32 s77, 61
	s_cbranch_scc0 .LBB0_1371
	s_add_u32 s56, s53, 0xffffff00
	s_addc_u32 s57, s72, -1
	s_andn2_b64 vcc, exec, s[6:7]
	s_cbranch_vccnz .LBB0_1362
	v_mov_b32_e32 v4, 0
	s_mov_b32 s0, s48
	s_mov_b32 s8, s50
	s_mov_b64 s[18:19], s[54:55]
	s_mov_b32 s63, s52
	v_mov_b32_e32 v5, v4
	v_mov_b32_e32 v6, v4
	v_mov_b32_e32 v7, v4
	v_mov_b32_e32 v8, v4
	v_mov_b32_e32 v9, v4
	v_mov_b32_e32 v10, v4
	v_mov_b32_e32 v11, v4
	v_mov_b32_e32 v20, v4
	v_mov_b32_e32 v21, v4
	v_mov_b32_e32 v22, v4
	v_mov_b32_e32 v23, v4
	v_mov_b32_e32 v24, v4
	v_mov_b32_e32 v25, v4
	v_mov_b32_e32 v26, v4
	v_mov_b32_e32 v27, v4
	v_mov_b32_e32 v36, v4
	v_mov_b32_e32 v37, v4
	v_mov_b32_e32 v38, v4
	v_mov_b32_e32 v39, v4
	v_mov_b32_e32 v40, v4
	v_mov_b32_e32 v41, v4
	v_mov_b32_e32 v42, v4
	v_mov_b32_e32 v43, v4
	v_mov_b32_e32 v52, v4
	v_mov_b32_e32 v53, v4
	v_mov_b32_e32 v54, v4
	v_mov_b32_e32 v55, v4
	v_mov_b32_e32 v56, v4
	v_mov_b32_e32 v57, v4
	v_mov_b32_e32 v58, v4
	v_mov_b32_e32 v59, v4
	v_mov_b32_e32 v12, v4
	v_mov_b32_e32 v13, v4
	v_mov_b32_e32 v14, v4
	v_mov_b32_e32 v15, v4
	v_mov_b32_e32 v16, v4
	v_mov_b32_e32 v17, v4
	v_mov_b32_e32 v18, v4
	v_mov_b32_e32 v19, v4
	v_mov_b32_e32 v28, v4
	v_mov_b32_e32 v29, v4
	v_mov_b32_e32 v30, v4
	v_mov_b32_e32 v31, v4
	v_mov_b32_e32 v32, v4
	v_mov_b32_e32 v33, v4
	v_mov_b32_e32 v34, v4
	v_mov_b32_e32 v35, v4
	v_mov_b32_e32 v44, v4
	v_mov_b32_e32 v45, v4
	v_mov_b32_e32 v46, v4
	v_mov_b32_e32 v47, v4
	v_mov_b32_e32 v48, v4
	v_mov_b32_e32 v49, v4
	v_mov_b32_e32 v50, v4
	v_mov_b32_e32 v51, v4
	v_mov_b32_e32 v60, v4
	v_mov_b32_e32 v61, v4
	v_mov_b32_e32 v62, v4
	v_mov_b32_e32 v63, v4
	v_mov_b32_e32 v64, v4
	v_mov_b32_e32 v65, v4
	v_mov_b32_e32 v66, v4
	v_mov_b32_e32 v67, v4
	v_mov_b32_e32 v68, v4
	v_mov_b32_e32 v69, v4
	v_mov_b32_e32 v70, v4
	v_mov_b32_e32 v71, v4
	v_mov_b32_e32 v72, v4
	v_mov_b32_e32 v73, v4
	v_mov_b32_e32 v74, v4
	v_mov_b32_e32 v75, v4
	v_mov_b32_e32 v84, v4
	v_mov_b32_e32 v85, v4
	v_mov_b32_e32 v86, v4
	v_mov_b32_e32 v87, v4
	v_mov_b32_e32 v88, v4
	v_mov_b32_e32 v89, v4
	v_mov_b32_e32 v90, v4
	v_mov_b32_e32 v91, v4
	v_mov_b32_e32 v100, v4
	v_mov_b32_e32 v101, v4
	v_mov_b32_e32 v102, v4
	v_mov_b32_e32 v103, v4
	v_mov_b32_e32 v104, v4
	v_mov_b32_e32 v105, v4
	v_mov_b32_e32 v106, v4
	v_mov_b32_e32 v107, v4
	v_mov_b32_e32 v116, v4
	v_mov_b32_e32 v117, v4
	v_mov_b32_e32 v118, v4
	v_mov_b32_e32 v119, v4
	v_mov_b32_e32 v120, v4
	v_mov_b32_e32 v121, v4
	v_mov_b32_e32 v122, v4
	v_mov_b32_e32 v123, v4
	v_mov_b32_e32 v76, v4
	v_mov_b32_e32 v77, v4
	v_mov_b32_e32 v78, v4
	v_mov_b32_e32 v79, v4
	v_mov_b32_e32 v80, v4
	v_mov_b32_e32 v81, v4
	v_mov_b32_e32 v82, v4
	v_mov_b32_e32 v83, v4
	v_mov_b32_e32 v92, v4
	v_mov_b32_e32 v93, v4
	v_mov_b32_e32 v94, v4
	v_mov_b32_e32 v95, v4
	v_mov_b32_e32 v96, v4
	v_mov_b32_e32 v97, v4
	v_mov_b32_e32 v98, v4
	v_mov_b32_e32 v99, v4
	v_mov_b32_e32 v108, v4
	v_mov_b32_e32 v109, v4
	v_mov_b32_e32 v110, v4
	v_mov_b32_e32 v111, v4
	v_mov_b32_e32 v112, v4
	v_mov_b32_e32 v113, v4
	v_mov_b32_e32 v114, v4
	v_mov_b32_e32 v115, v4
	v_mov_b32_e32 v124, v4
	v_mov_b32_e32 v125, v4
	v_mov_b32_e32 v126, v4
	v_mov_b32_e32 v127, v4
	v_mov_b32_e32 v128, v4
	v_mov_b32_e32 v129, v4
	v_mov_b32_e32 v130, v4
	v_mov_b32_e32 v131, v4
	s_andn2_b64 vcc, exec, s[4:5]
	s_cbranch_vccnz .LBB0_1363
